# qkv conv phase: next item's 19 rows prefetched into spare VGPRs, conv taps staged in LDS, counted vmcnt leaves stores in flight (on top of scan DMA + prep2)
# speedup vs baseline: 1.0109x; 1.0062x over previous
; __device__ __forceinline__ void phase_qkv(const Args& a) {
;     const int tid = threadIdx.x, lane = tid & 63, wave = tid >> 6;
;     const bf16_t* proj = (const bf16_t*)(a.ws + WS_PROJ); const float* cw = a.in[3];
;     for (int item = blockIdx.x * 8 + wave; item < 6144; item += gridDim.x * 8) {
;         const int part = item % 3, rg = item / 3, rowA = rg * 16, pos0 = rowA & 2047, ch0 = part * 512 + 8 * lane;
;         float w[4][8];
; #pragma unroll
;         for (int i = 0; i < 4; ++i) { const f32x4 w0 = *(const f32x4*)(cw + i * 1536 + ch0), w1 = *(const f32x4*)(cw + i * 1536 + ch0 + 4);
;             w[i][0] = w0[0]; w[i][1] = w0[1]; w[i][2] = w0[2]; w[i][3] = w0[3]; w[i][4] = w1[0]; w[i][5] = w1[1]; w[i][6] = w1[2]; w[i][7] = w1[3]; }
;         u32x4 R[19];
; #pragma unroll
;         for (int j = 0; j < 19; ++j) { const int dr = j - 3; const int rr = (pos0 + dr >= 0) ? rowA + dr : rowA; R[j] = *(const u32x4*)(proj + (size_t)rr * NPROJ + ch0); }
.LBB0_126:
	s_or_b64 exec, exec, s[0:1]
	v_readlane_b32 s0, v253, 17
	s_bitcmp0_b32 s0, 2
	v_lshrrev_b32_e32 v153, 6, v152
	s_waitcnt lgkmcnt(0)
	s_barrier
	s_cbranch_scc1 .LBB0_197
	v_readlane_b32 s42, v253, 7
	v_readlane_b32 s43, v253, 8
	v_lshlrev_b32_e32 v248, 4, v152
	v_add_u32_e32 v249, 0x2000, v248
	v_add_u32_e32 v250, 0x4000, v248
	s_nop 4
	global_load_dwordx4 v[172:175], v248, s[42:43]
	global_load_dwordx4 v[176:179], v249, s[42:43]
	global_load_dwordx4 v[180:183], v250, s[42:43]
	s_waitcnt vmcnt(0)
	ds_write_b128 v248, v[172:175]
	ds_write_b128 v248, v[176:179] offset:8192
	ds_write_b128 v248, v[180:183] offset:16384
	s_waitcnt lgkmcnt(0)
	s_barrier
	v_and_b32_e32 v248, 63, v152
	v_lshlrev_b32_e32 v248, 4, v248
	v_lshl_add_u32 v96, s82, 3, v153
	s_movk_i32 s0, 0x1800
	v_cmp_gt_i32_e32 vcc, s0, v96
	s_and_saveexec_b64 s[6:7], vcc
	s_cbranch_execz .LBB0_196
	v_lshlrev_b32_e32 v0, 3, v152
	v_lshlrev_b32_e32 v1, 9, v153
	v_and_b32_e32 v0, 0x1f8, v0
	v_mov_b32_e32 v99, 0
	v_lshl_add_u32 v1, s82, 12, v1
	v_lshlrev_b32_e32 v100, 7, v0
	v_mov_b32_e32 v101, v99
	s_lshl_b32 s20, s80, 3
	v_or_b32_e32 v102, v1, v0
	s_lshl_b32 s21, s80, 12
	s_mov_b64 s[8:9], 0
	s_mov_b32 s22, 0x55555556
	s_movk_i32 s23, 0xfa00
	s_mov_b64 s[10:11], 0x1800
	s_movk_i32 s24, 0x1000
	s_mov_b64 s[12:13], 0x3000
	s_movk_i32 s25, 0x3000
	s_mov_b64 s[14:15], 0x4800
	s_movk_i32 s26, 0x4000
	s_movk_i32 s27, 0x1400
	v_mov_b32_e32 v97, 0x3db504f3
	s_mov_b32 s28, 0xffff0000
	s_mov_b32 s29, 0x800000
	v_lshlrev_b32_e32 v104, 1, v0
	s_movk_i32 s30, 0x17ff
	v_mov_b32_e32 v103, 0x12000000
	v_bfrev_b32_e32 v162, 8
	v_bfrev_b32_e32 v163, 32
	v_bfrev_b32_e32 v164, 64
	v_readfirstlane_b32 s90, v96
	s_mov_b32 s101, 0
	s_mov_b32 s91, s90
	s_mul_hi_u32 s92, s91, 0x55555556
	s_mul_i32 s93, s92, 3
	s_sub_u32 s93, s91, s93
	s_mul_i32 s94, s92, 0x14000
	s_lshl_b32 s95, s93, 10
	s_add_u32 s94, s94, s95
	s_add_u32 s96, s2, s94
	s_addc_u32 s97, s3, 0
	s_and_b32 s95, s92, 0x7f
	s_cmp_eq_u32 s95, 0
	s_cselect_b32 s95, 0, 0x1400
	s_mul_i32 s100, s95, 3
	s_sub_u32 s98, s96, s100
	s_subb_u32 s99, s97, 0
	global_load_dwordx4 v[172:175], v248, s[98:99]
	s_add_u32 s98, s98, s95
	s_addc_u32 s99, s99, 0
	global_load_dwordx4 v[176:179], v248, s[98:99]
	s_add_u32 s98, s98, s95
	s_addc_u32 s99, s99, 0
	global_load_dwordx4 v[180:183], v248, s[98:99]
	global_load_dwordx4 v[184:187], v248, s[96:97]
	s_add_u32 s96, s96, 0x1400
	s_addc_u32 s97, s97, 0
	global_load_dwordx4 v[188:191], v248, s[96:97]
	s_add_u32 s96, s96, 0x1400
	s_addc_u32 s97, s97, 0
	global_load_dwordx4 v[192:195], v248, s[96:97]
	s_add_u32 s96, s96, 0x1400
	s_addc_u32 s97, s97, 0
	global_load_dwordx4 v[196:199], v248, s[96:97]
	s_add_u32 s96, s96, 0x1400
	s_addc_u32 s97, s97, 0
	global_load_dwordx4 v[200:203], v248, s[96:97]
	s_add_u32 s96, s96, 0x1400
	s_addc_u32 s97, s97, 0
	global_load_dwordx4 v[204:207], v248, s[96:97]
	s_add_u32 s96, s96, 0x1400
	s_addc_u32 s97, s97, 0
	global_load_dwordx4 v[208:211], v248, s[96:97]
	s_add_u32 s96, s96, 0x1400
	s_addc_u32 s97, s97, 0
	global_load_dwordx4 v[212:215], v248, s[96:97]
	s_add_u32 s96, s96, 0x1400
	s_addc_u32 s97, s97, 0
	global_load_dwordx4 v[216:219], v248, s[96:97]
	s_add_u32 s96, s96, 0x1400
	s_addc_u32 s97, s97, 0
	global_load_dwordx4 v[220:223], v248, s[96:97]
	s_add_u32 s96, s96, 0x1400
	s_addc_u32 s97, s97, 0
	global_load_dwordx4 v[224:227], v248, s[96:97]
	s_add_u32 s96, s96, 0x1400
	s_addc_u32 s97, s97, 0
	global_load_dwordx4 v[228:231], v248, s[96:97]
	s_add_u32 s96, s96, 0x1400
	s_addc_u32 s97, s97, 0
	global_load_dwordx4 v[232:235], v248, s[96:97]
	s_add_u32 s96, s96, 0x1400
	s_addc_u32 s97, s97, 0
	global_load_dwordx4 v[236:239], v248, s[96:97]
	s_add_u32 s96, s96, 0x1400
	s_addc_u32 s97, s97, 0
	global_load_dwordx4 v[240:243], v248, s[96:97]
	s_add_u32 s96, s96, 0x1400
	s_addc_u32 s97, s97, 0
	global_load_dwordx4 v[244:247], v248, s[96:97]
	s_branch .LBB0_130
.LBB0_129:
	s_or_b64 exec, exec, s[0:1]
	s_add_u32 s90, s90, s20
	v_add_u32_e32 v96, s20, v96
	v_cmp_lt_i32_e32 vcc, s30, v96
	s_or_b64 s[8:9], vcc, s[8:9]
	v_add_u32_e32 v102, s21, v102
	s_andn2_b64 exec, exec, s[8:9]
	s_cbranch_execz .LBB0_196
.LBB0_130:
	v_mul_hi_i32 v0, v96, s22
	v_lshrrev_b32_e32 v1, 31, v0
	v_add_u32_e32 v165, v0, v1
	v_mad_u64_u32 v[16:17], s[0:1], v165, s23, v[102:103]
	v_lshlrev_b32_e32 v249, 2, v16
	v_readlane_b32 s36, v253, 1
	v_ashrrev_i32_e32 v17, 31, v16
	v_readlane_b32 s42, v253, 7
	v_readlane_b32 s43, v253, 8
	v_lshlrev_b32_e32 v106, 4, v165
	v_and_b32_e32 v46, 0x7f0, v106
	v_lshl_add_u64 v[8:9], v[16:17], 2, s[42:43]
	v_add_co_u32_e32 v4, vcc, s24, v8
	v_lshl_add_u64 v[10:11], v[8:9], 0, s[10:11]
	s_nop 0
	v_addc_co_u32_e32 v5, vcc, 0, v9, vcc
	v_add_co_u32_e32 v12, vcc, s25, v8
	ds_read_b128 v[20:23], v249 offset:16
	ds_read_b128 v[0:3], v249
	v_addc_co_u32_e32 v13, vcc, 0, v9, vcc
	ds_read_b128 v[4:7], v249 offset:6144
	s_nop 0
	ds_read_b128 v[24:27], v249 offset:6160
	v_lshl_add_u64 v[10:11], v[8:9], 0, s[12:13]
	v_lshl_add_u64 v[18:19], v[8:9], 0, s[14:15]
	v_add_co_u32_e32 v8, vcc, s26, v8
	v_lshl_add_u64 v[36:37], v[16:17], 1, s[2:3]
	s_nop 0
	v_addc_co_u32_e32 v9, vcc, 0, v9, vcc
	v_or_b32_e32 v38, 1, v106
	v_mad_i64_i32 v[16:17], s[0:1], v106, s27, v[36:37]
	v_mad_i64_i32 v[38:39], s[0:1], v38, s27, v[36:37]
	v_cmp_ne_u32_e32 vcc, 0, v46
	v_cmp_eq_u32_e64 s[4:5], 0, v46
	ds_read_b128 v[12:15], v249 offset:12288
	s_nop 0
	ds_read_b128 v[28:31], v249 offset:12304
	s_nop 0
	ds_read_b128 v[8:11], v249 offset:18432
	s_nop 0
	ds_read_b128 v[32:35], v249 offset:18448
	v_subbrev_co_u32_e32 v38, vcc, 0, v106, vcc
	v_cndmask_b32_e64 v46, -2, 0, s[4:5]
	v_or_b32_e32 v44, 2, v106
; __device__ __forceinline__ void phase_qkv(const Args& a) {
;     ...
;         u32x4 R[19];
; #pragma unroll
;         for (int j = 0; j < 19; ++j) { const int dr = j - 3; const int rr = (pos0 + dr >= 0) ? rowA + dr : rowA; R[j] = *(const u32x4*)(proj + (size_t)rr * NPROJ + ch0); }
	v_mad_i64_i32 v[38:39], s[0:1], v38, s27, v[36:37]
	v_add_u32_e32 v46, v46, v106
	v_mad_i64_i32 v[38:39], s[0:1], v44, s27, v[36:37]
	v_or_b32_e32 v44, 3, v106
	v_mad_i64_i32 v[46:47], s[0:1], v46, s27, v[36:37]
	v_mad_i64_i32 v[44:45], s[0:1], v44, s27, v[36:37]
	v_cndmask_b32_e64 v46, -3, 0, s[4:5]
	v_add_u32_e32 v46, v46, v106
	v_or_b32_e32 v38, 4, v106
	v_or_b32_e32 v44, 5, v106
	v_mad_i64_i32 v[46:47], s[0:1], v46, s27, v[36:37]
	v_mad_i64_i32 v[38:39], s[0:1], v38, s27, v[36:37]
	v_mad_i64_i32 v[44:45], s[0:1], v44, s27, v[36:37]
	v_or_b32_e32 v38, 6, v106
	v_or_b32_e32 v44, 7, v106
	v_mad_i64_i32 v[38:39], s[0:1], v38, s27, v[36:37]
	v_mad_i64_i32 v[44:45], s[0:1], v44, s27, v[36:37]
	v_or_b32_e32 v38, 8, v106
	v_or_b32_e32 v44, 9, v106
	v_mad_i64_i32 v[38:39], s[0:1], v38, s27, v[36:37]
	v_mad_i64_i32 v[44:45], s[0:1], v44, s27, v[36:37]
	v_or_b32_e32 v38, 10, v106
	v_or_b32_e32 v44, 11, v106
	v_mad_i64_i32 v[38:39], s[0:1], v38, s27, v[36:37]
	v_mad_i64_i32 v[44:45], s[0:1], v44, s27, v[36:37]
	v_or_b32_e32 v38, 12, v106
	v_or_b32_e32 v44, 13, v106
	v_mad_i64_i32 v[38:39], s[0:1], v38, s27, v[36:37]
	v_mad_i64_i32 v[44:45], s[0:1], v44, s27, v[36:37]
	v_or_b32_e32 v38, 14, v106
	v_or_b32_e32 v44, 15, v106
	v_mad_i64_i32 v[38:39], s[0:1], v38, s27, v[36:37]
	v_mad_i64_i32 v[36:37], s[0:1], v44, s27, v[36:37]
	s_nop 0
	v_mad_u64_u32 v[108:109], s[0:1], v165, -3, v[96:97]
	v_subrev_co_u32_e32 v109, vcc, 1, v108
	v_cmp_gt_i32_e64 s[0:1], 2, v108
	s_nop 0
	v_cndmask_b32_e32 v166, 1.0, v97, vcc
	v_readlane_b32 s37, v253, 2
	v_readlane_b32 s38, v253, 3
	v_readlane_b32 s39, v253, 4
	v_readlane_b32 s40, v253, 5
	v_readlane_b32 s41, v253, 6
	v_readlane_b32 s44, v253, 9
	v_readlane_b32 s45, v253, 10
	v_readlane_b32 s46, v253, 11
	v_readlane_b32 s47, v253, 12
	v_readlane_b32 s48, v253, 13
	v_readlane_b32 s49, v253, 14
	v_readlane_b32 s50, v253, 15
	v_readlane_b32 s51, v253, 16
	s_cmp_eq_u32 s101, 1
	s_cbranch_scc1 .Lqk_w16
	s_cmp_eq_u32 s101, 2
	s_cbranch_scc1 .Lqk_w32
	s_waitcnt vmcnt(0)
	s_branch .Lqk_wd
.Lqk_w16:
	s_waitcnt vmcnt(16)
	s_branch .Lqk_wd
.Lqk_w32:
	s_waitcnt vmcnt(32)
.Lqk_wd:
	v_mov_b64_e32 v[168:169], v[172:173]
	v_mov_b64_e32 v[170:171], v[174:175]
	v_mov_b64_e32 v[146:147], v[176:177]
	v_mov_b64_e32 v[148:149], v[178:179]
	v_mov_b64_e32 v[122:123], v[180:181]
	v_mov_b64_e32 v[124:125], v[182:183]
	v_mov_b64_e32 v[16:17], v[184:185]
	v_mov_b64_e32 v[18:19], v[186:187]
	v_mov_b64_e32 v[40:41], v[188:189]
	v_mov_b64_e32 v[42:43], v[190:191]
	v_mov_b64_e32 v[48:49], v[192:193]
	v_mov_b64_e32 v[50:51], v[194:195]
	v_mov_b64_e32 v[56:57], v[196:197]
	v_mov_b64_e32 v[58:59], v[198:199]
	v_mov_b64_e32 v[64:65], v[200:201]
	v_mov_b64_e32 v[66:67], v[202:203]
	v_mov_b64_e32 v[72:73], v[204:205]
	v_mov_b64_e32 v[74:75], v[206:207]
	v_mov_b64_e32 v[80:81], v[208:209]
	v_mov_b64_e32 v[82:83], v[210:211]
	v_mov_b64_e32 v[88:89], v[212:213]
	v_mov_b64_e32 v[90:91], v[214:215]
	v_mov_b64_e32 v[92:93], v[216:217]
	v_mov_b64_e32 v[94:95], v[218:219]
	v_mov_b64_e32 v[84:85], v[220:221]
	v_mov_b64_e32 v[86:87], v[222:223]
	v_mov_b64_e32 v[76:77], v[224:225]
	v_mov_b64_e32 v[78:79], v[226:227]
	v_mov_b64_e32 v[68:69], v[228:229]
	v_mov_b64_e32 v[70:71], v[230:231]
	v_mov_b64_e32 v[60:61], v[232:233]
	v_mov_b64_e32 v[62:63], v[234:235]
	v_mov_b64_e32 v[52:53], v[236:237]
	v_mov_b64_e32 v[54:55], v[238:239]
	v_mov_b64_e32 v[44:45], v[240:241]
	v_mov_b64_e32 v[46:47], v[242:243]
	v_mov_b64_e32 v[36:37], v[244:245]
	v_mov_b64_e32 v[38:39], v[246:247]
	s_mul_hi_u32 s92, s90, 0x55555556
	s_mul_i32 s93, s92, 3
	s_sub_u32 s93, s90, s93
	s_cmp_eq_u32 s93, 1
	s_cselect_b32 s101, 2, 1
	s_add_u32 s91, s90, s20
	s_cmp_lt_u32 s91, 0x1800
	s_cbranch_scc0 .Lqk_nopf
	s_mul_hi_u32 s92, s91, 0x55555556
	s_mul_i32 s93, s92, 3
	s_sub_u32 s93, s91, s93
	s_mul_i32 s94, s92, 0x14000
	s_lshl_b32 s95, s93, 10
	s_add_u32 s94, s94, s95
	s_add_u32 s96, s2, s94
	s_addc_u32 s97, s3, 0
	s_and_b32 s95, s92, 0x7f
	s_cmp_eq_u32 s95, 0
	s_cselect_b32 s95, 0, 0x1400
	s_mul_i32 s100, s95, 3
	s_sub_u32 s98, s96, s100
	s_subb_u32 s99, s97, 0
	global_load_dwordx4 v[172:175], v248, s[98:99]
	s_add_u32 s98, s98, s95
	s_addc_u32 s99, s99, 0
	global_load_dwordx4 v[176:179], v248, s[98:99]
	s_add_u32 s98, s98, s95
	s_addc_u32 s99, s99, 0
	global_load_dwordx4 v[180:183], v248, s[98:99]
	global_load_dwordx4 v[184:187], v248, s[96:97]
	s_add_u32 s96, s96, 0x1400
	s_addc_u32 s97, s97, 0
	global_load_dwordx4 v[188:191], v248, s[96:97]
	s_add_u32 s96, s96, 0x1400
	s_addc_u32 s97, s97, 0
	global_load_dwordx4 v[192:195], v248, s[96:97]
	s_add_u32 s96, s96, 0x1400
	s_addc_u32 s97, s97, 0
	global_load_dwordx4 v[196:199], v248, s[96:97]
	s_add_u32 s96, s96, 0x1400
	s_addc_u32 s97, s97, 0
	global_load_dwordx4 v[200:203], v248, s[96:97]
	s_add_u32 s96, s96, 0x1400
	s_addc_u32 s97, s97, 0
	global_load_dwordx4 v[204:207], v248, s[96:97]
	s_add_u32 s96, s96, 0x1400
	s_addc_u32 s97, s97, 0
	global_load_dwordx4 v[208:211], v248, s[96:97]
	s_add_u32 s96, s96, 0x1400
	s_addc_u32 s97, s97, 0
	global_load_dwordx4 v[212:215], v248, s[96:97]
	s_add_u32 s96, s96, 0x1400
	s_addc_u32 s97, s97, 0
	global_load_dwordx4 v[216:219], v248, s[96:97]
	s_add_u32 s96, s96, 0x1400
	s_addc_u32 s97, s97, 0
	global_load_dwordx4 v[220:223], v248, s[96:97]
	s_add_u32 s96, s96, 0x1400
	s_addc_u32 s97, s97, 0
	global_load_dwordx4 v[224:227], v248, s[96:97]
	s_add_u32 s96, s96, 0x1400
	s_addc_u32 s97, s97, 0
	global_load_dwordx4 v[228:231], v248, s[96:97]
	s_add_u32 s96, s96, 0x1400
	s_addc_u32 s97, s97, 0
	global_load_dwordx4 v[232:235], v248, s[96:97]
	s_add_u32 s96, s96, 0x1400
	s_addc_u32 s97, s97, 0
	global_load_dwordx4 v[236:239], v248, s[96:97]
	s_add_u32 s96, s96, 0x1400
	s_addc_u32 s97, s97, 0
	global_load_dwordx4 v[240:243], v248, s[96:97]
	s_add_u32 s96, s96, 0x1400
	s_addc_u32 s97, s97, 0
	global_load_dwordx4 v[244:247], v248, s[96:97]
; __device__ __forceinline__ void unpack8(const u32x4 w, float (&f)[8]) { f[0] = bf_lo(w.x); f[1] = bf_hi(w.x); f[2] = bf_lo(w.y); f[3] = bf_hi(w.y); f[4] = bf_lo(w.z); f[5] = bf_hi(w.z); f[6] = bf_lo(w.w); f[7] = bf_hi(w.w); }
; __device__ __forceinline__ float siluf_(float x) { return x * __builtin_amdgcn_rcpf(1.0f + __builtin_amdgcn_exp2f(x * -1.4426950408889634f)); }
; __device__ __forceinline__ void phase_qkv(const Args& a) {
;     ...
;         for (int m = 0; m < 16; ++m) {
;             float acc[8];
; #pragma unroll
;             for (int e = 0; e < 8; ++e) acc[e] = 0.f;
;             if (m == 0) { unpack8(R[0], F[0]); unpack8(R[1], F[1]); unpack8(R[2], F[2]); }
;             unpack8(R[m + 3], F[m + 3]);
; #pragma unroll
;             for (int i = 0; i < 4; ++i) {
;                 if (m + i < 3) { const float vm = (pos0 + m + i - 3 >= 0) ? 1.0f : 0.0f;
; #pragma unroll
;                     for (int e = 0; e < 8; ++e) acc[e] += F[m + i][e] * (w[i][e] * vm); }
;                 else {
; #pragma unroll
;                     for (int e = 0; e < 8; ++e) acc[e] += F[m + i][e] * w[i][e]; } }
;             float ssq = 0.f;
; #pragma unroll
;             for (int e = 0; e < 8; ++e) { acc[e] = siluf_(acc[e]); ssq += acc[e] * acc[e]; }
;             if (part < 2) { ssq = sum16(ssq); const float sc = rsqrtf(ssq + EPS) * qsc;
; #pragma unroll
;                 for (int e = 0; e < 8; ++e) acc[e] *= sc; }
.Lqk_nopf:
	s_waitcnt lgkmcnt(0)
	v_and_b32_e32 v113, 0xffff0000, v16
	v_lshlrev_b32_e32 v112, 16, v16
	v_cndmask_b32_e64 v16, 1.0, 0, s[4:5]
	v_and_b32_e32 v117, 0xffff0000, v18
	v_lshlrev_b32_e32 v116, 16, v18
	v_and_b32_e32 v119, 0xffff0000, v19
	v_lshlrev_b32_e32 v118, 16, v19
	v_pk_mul_f32 v[150:151], v[22:23], v[16:17] op_sel_hi:[1,0]
	v_pk_mul_f32 v[160:161], v[16:17], v[26:27] op_sel_hi:[0,1]
	v_and_b32_e32 v145, 0xffff0000, v125
	v_lshlrev_b32_e32 v144, 16, v125
	v_pk_mul_f32 v[110:111], v[16:17], v[30:31] op_sel_hi:[0,1]
	v_and_b32_e32 v159, 0xffff0000, v149
	v_lshlrev_b32_e32 v158, 16, v149
	v_pk_mul_f32 v[142:143], v[20:21], v[16:17] op_sel_hi:[1,0]
	v_and_b32_e32 v155, 0xffff0000, v148
	v_lshlrev_b32_e32 v154, 16, v148
	v_pk_mul_f32 v[156:157], v[16:17], v[24:25] op_sel_hi:[0,1]
	v_and_b32_e32 v137, 0xffff0000, v124
	v_lshlrev_b32_e32 v136, 16, v124
	v_pk_mul_f32 v[124:125], v[16:17], v[28:29] op_sel_hi:[0,1]
	v_pk_mul_f32 v[134:135], v[2:3], v[16:17] op_sel_hi:[1,0]
	v_and_b32_e32 v121, 0xffff0000, v122
	v_and_b32_e32 v19, 0xffff0000, v171
	v_lshlrev_b32_e32 v18, 16, v171
	v_pk_fma_f32 v[18:19], v[150:151], v[18:19], 0 op_sel_hi:[1,1,0]
	v_lshlrev_b32_e32 v120, 16, v122
	v_pk_fma_f32 v[18:19], v[160:161], v[158:159], v[18:19]
	v_and_b32_e32 v129, 0xffff0000, v123
	v_pk_fma_f32 v[18:19], v[110:111], v[144:145], v[18:19]
	v_lshlrev_b32_e32 v128, 16, v123
	v_pk_fma_f32 v[110:111], v[34:35], v[118:119], v[18:19]
	v_and_b32_e32 v19, 0xffff0000, v170
	v_lshlrev_b32_e32 v18, 16, v170
	v_pk_fma_f32 v[18:19], v[142:143], v[18:19], 0 op_sel_hi:[1,1,0]
	v_and_b32_e32 v123, 0xffff0000, v146
	v_pk_fma_f32 v[18:19], v[156:157], v[154:155], v[18:19]
	v_lshlrev_b32_e32 v122, 16, v146
	v_pk_fma_f32 v[18:19], v[124:125], v[136:137], v[18:19]
	v_and_b32_e32 v125, 0xffff0000, v169
	v_lshlrev_b32_e32 v124, 16, v169
	v_and_b32_e32 v139, 0xffff0000, v147
	v_lshlrev_b32_e32 v138, 16, v147
	v_pk_mul_f32 v[146:147], v[6:7], v[16:17] op_sel_hi:[1,0]
	v_pk_fma_f32 v[124:125], v[134:135], v[124:125], 0 op_sel_hi:[1,1,0]
	v_pk_mul_f32 v[132:133], v[16:17], v[14:15] op_sel_hi:[0,1]
	v_pk_fma_f32 v[124:125], v[146:147], v[138:139], v[124:125]
	v_pk_mul_f32 v[126:127], v[0:1], v[16:17] op_sel_hi:[1,0]
	v_pk_fma_f32 v[124:125], v[132:133], v[128:129], v[124:125]
	v_and_b32_e32 v133, 0xffff0000, v168
	v_lshlrev_b32_e32 v132, 16, v168
	v_pk_mul_f32 v[130:131], v[4:5], v[16:17] op_sel_hi:[1,0]
	v_pk_fma_f32 v[132:133], v[126:127], v[132:133], 0 op_sel_hi:[1,1,0]
	v_and_b32_e32 v115, 0xffff0000, v17
	v_lshlrev_b32_e32 v114, 16, v17
	v_pk_fma_f32 v[132:133], v[130:131], v[122:123], v[132:133]
	v_pk_mul_f32 v[16:17], v[16:17], v[12:13] op_sel_hi:[0,1]
	v_pk_fma_f32 v[16:17], v[16:17], v[120:121], v[132:133]
	v_pk_fma_f32 v[124:125], v[10:11], v[114:115], v[124:125]
	v_pk_fma_f32 v[16:17], v[8:9], v[112:113], v[16:17]
	v_mul_f32_e32 v107, 0xbfb8aa3b, v125
	v_mul_f32_e32 v98, 0xbfb8aa3b, v16
	v_exp_f32_e32 v98, v98
	v_mul_f32_e32 v105, 0xbfb8aa3b, v17
	v_exp_f32_e32 v105, v105
	v_exp_f32_e32 v107, v107
	v_add_f32_e32 v98, 1.0, v98
	v_rcp_f32_e32 v132, v98
	v_add_f32_e32 v98, 1.0, v105
	v_mul_f32_e32 v105, 0xbfb8aa3b, v124
	v_exp_f32_e32 v105, v105
	v_pk_fma_f32 v[18:19], v[32:33], v[116:117], v[18:19]
	v_rcp_f32_e32 v133, v98
	v_add_f32_e32 v98, 1.0, v105
	v_mul_f32_e32 v105, 0xbfb8aa3b, v18
	v_rcp_f32_e32 v140, v98
	v_add_f32_e32 v98, 1.0, v107
	v_exp_f32_e32 v105, v105
	v_mul_f32_e32 v107, 0xbfb8aa3b, v19
	v_exp_f32_e32 v107, v107
	v_rcp_f32_e32 v141, v98
	v_add_f32_e32 v98, 1.0, v105
	v_mul_f32_e32 v105, 0xbfb8aa3b, v110
	v_rcp_f32_e32 v148, v98
	v_add_f32_e32 v98, 1.0, v107
	v_exp_f32_e32 v105, v105
	v_mul_f32_e32 v107, 0xbfb8aa3b, v111
	v_exp_f32_e32 v107, v107
	v_rcp_f32_e32 v149, v98
	v_add_f32_e32 v98, 1.0, v105
	v_rcp_f32_e32 v168, v98
	v_add_f32_e32 v98, 1.0, v107
	v_rcp_f32_e32 v169, v98
	v_pk_mul_f32 v[16:17], v[16:17], v[132:133]
	v_pk_mul_f32 v[132:133], v[124:125], v[140:141]
	v_pk_mul_f32 v[18:19], v[18:19], v[148:149]
	v_pk_mul_f32 v[124:125], v[110:111], v[168:169]
	s_and_saveexec_b64 s[18:19], s[0:1]
	s_cbranch_execz .LBB0_132
	v_pk_mul_f32 v[110:111], v[16:17], v[16:17]
	v_pk_mul_f32 v[140:141], v[132:133], v[132:133]
	v_add_f32_e32 v98, v110, v111
	v_add_f32_e32 v98, v140, v98
	v_pk_mul_f32 v[148:149], v[18:19], v[18:19]
	v_add_f32_e32 v98, v141, v98
	v_add_f32_e32 v98, v148, v98
	v_pk_mul_f32 v[168:169], v[124:125], v[124:125]
	v_add_f32_e32 v98, v149, v98
	v_add_f32_e32 v98, v168, v98
	v_add_f32_e32 v98, v169, v98
	s_nop 1
	v_add_f32_dpp v98, v98, v98 row_ror:8 row_mask:0xf bank_mask:0xf bound_ctrl:1
	s_nop 1
	v_add_f32_dpp v98, v98, v98 row_ror:4 row_mask:0xf bank_mask:0xf bound_ctrl:1
	s_nop 1
	v_add_f32_dpp v98, v98, v98 row_ror:2 row_mask:0xf bank_mask:0xf bound_ctrl:1
	s_nop 1
	v_add_f32_dpp v98, v98, v98 row_ror:1 row_mask:0xf bank_mask:0xf bound_ctrl:1
	v_add_f32_e32 v98, 0x358637bd, v98
	v_mul_f32_e32 v105, 0x4b800000, v98
	v_cmp_gt_f32_e64 s[4:5], s29, v98
	s_nop 1
	v_cndmask_b32_e64 v98, v98, v105, s[4:5]
	v_rsq_f32_e32 v98, v98
	s_nop 0
	v_mul_f32_e32 v105, 0x45800000, v98
	v_cndmask_b32_e64 v98, v98, v105, s[4:5]
	v_mul_f32_e32 v98, v166, v98
	v_pk_mul_f32 v[16:17], v[16:17], v[98:99] op_sel_hi:[1,0]
	v_pk_mul_f32 v[132:133], v[132:133], v[98:99] op_sel_hi:[1,0]
	v_pk_mul_f32 v[18:19], v[18:19], v[98:99] op_sel_hi:[1,0]
	v_pk_mul_f32 v[124:125], v[124:125], v[98:99] op_sel_hi:[1,0]

; __device__ __forceinline__ void unpack8(const u32x4 w, float (&f)[8]) { f[0] = bf_lo(w.x); f[1] = bf_hi(w.x); f[2] = bf_lo(w.y); f[3] = bf_hi(w.y); f[4] = bf_lo(w.z); f[5] = bf_hi(w.z); f[6] = bf_lo(w.w); f[7] = bf_hi(w.w); }
; __device__ __forceinline__ float siluf_(float x) { return x * __builtin_amdgcn_rcpf(1.0f + __builtin_amdgcn_exp2f(x * -1.4426950408889634f)); }
; __device__ __forceinline__ void phase_qkv(const Args& a) {
;     ...
;         for (int m = 0; m < 16; ++m) {
;             float acc[8];
; #pragma unroll
;             for (int e = 0; e < 8; ++e) acc[e] = 0.f;
;             if (m == 0) { unpack8(R[0], F[0]); unpack8(R[1], F[1]); unpack8(R[2], F[2]); }
;             unpack8(R[m + 3], F[m + 3]);
; #pragma unroll
;             for (int i = 0; i < 4; ++i) {
;                 if (m + i < 3) { const float vm = (pos0 + m + i - 3 >= 0) ? 1.0f : 0.0f;
; #pragma unroll
;                     for (int e = 0; e < 8; ++e) acc[e] += F[m + i][e] * (w[i][e] * vm); }
;                 else {
; #pragma unroll
;                     for (int e = 0; e < 8; ++e) acc[e] += F[m + i][e] * w[i][e]; } }
;             float ssq = 0.f;
; #pragma unroll
;             for (int e = 0; e < 8; ++e) { acc[e] = siluf_(acc[e]); ssq += acc[e] * acc[e]; }
;             if (part < 2) { ssq = sum16(ssq); const float sc = rsqrtf(ssq + EPS) * qsc;
; #pragma unroll
;                 for (int e = 0; e < 8; ++e) acc[e] *= sc; }
.LBB0_146:
	s_or_b64 exec, exec, s[4:5]
	v_and_b32_e32 v113, 0xffff0000, v64
	v_lshlrev_b32_e32 v112, 16, v64
	v_and_b32_e32 v127, 0xffff0000, v65
	v_lshlrev_b32_e32 v126, 16, v65
	v_pk_fma_f32 v[64:65], v[22:23], v[148:149], 0 op_sel_hi:[1,1,0]
	v_pk_fma_f32 v[116:117], v[0:1], v[124:125], 0 op_sel_hi:[1,1,0]
	v_pk_fma_f32 v[64:65], v[26:27], v[146:147], v[64:65]
	v_and_b32_e32 v143, 0xffff0000, v67
	v_lshlrev_b32_e32 v142, 16, v67
	v_pk_fma_f32 v[64:65], v[30:31], v[144:145], v[64:65]
	v_pk_fma_f32 v[116:117], v[4:5], v[122:123], v[116:117]
	v_pk_fma_f32 v[114:115], v[34:35], v[142:143], v[64:65]
	v_pk_fma_f32 v[64:65], v[20:21], v[140:141], 0 op_sel_hi:[1,1,0]
	v_pk_fma_f32 v[116:117], v[12:13], v[120:121], v[116:117]
	v_pk_fma_f32 v[64:65], v[24:25], v[138:139], v[64:65]
	v_pk_fma_f32 v[116:117], v[8:9], v[112:113], v[116:117]
	v_and_b32_e32 v135, 0xffff0000, v66
	v_lshlrev_b32_e32 v134, 16, v66
	v_pk_fma_f32 v[64:65], v[28:29], v[136:137], v[64:65]
	v_mul_f32_e32 v98, 0xbfb8aa3b, v116
	v_pk_fma_f32 v[66:67], v[32:33], v[134:135], v[64:65]
	v_pk_fma_f32 v[64:65], v[2:3], v[132:133], 0 op_sel_hi:[1,1,0]
	v_exp_f32_e32 v98, v98
	v_mul_f32_e32 v105, 0xbfb8aa3b, v117
	v_pk_fma_f32 v[64:65], v[6:7], v[130:131], v[64:65]
	v_exp_f32_e32 v105, v105
	v_pk_fma_f32 v[64:65], v[14:15], v[128:129], v[64:65]
	v_mul_f32_e32 v107, 0xbfb8aa3b, v67
	v_pk_fma_f32 v[118:119], v[10:11], v[126:127], v[64:65]
	v_add_f32_e32 v64, 1.0, v98
	v_mul_f32_e32 v98, 0xbfb8aa3b, v118
	v_add_f32_e32 v65, 1.0, v105
	v_exp_f32_e32 v98, v98
	v_mul_f32_e32 v105, 0xbfb8aa3b, v119
	v_exp_f32_e32 v105, v105
	v_exp_f32_e32 v107, v107
	v_add_f32_e32 v98, 1.0, v98
	v_rcp_f32_e32 v124, v98
	v_add_f32_e32 v98, 1.0, v105
	v_mul_f32_e32 v105, 0xbfb8aa3b, v66
	v_exp_f32_e32 v105, v105
	v_rcp_f32_e32 v125, v98
	v_rcp_f32_e32 v64, v64
	v_rcp_f32_e32 v65, v65
	v_add_f32_e32 v98, 1.0, v105
	v_mul_f32_e32 v105, 0xbfb8aa3b, v114
	v_rcp_f32_e32 v132, v98
	v_add_f32_e32 v98, 1.0, v107
	v_exp_f32_e32 v105, v105
	v_mul_f32_e32 v107, 0xbfb8aa3b, v115
	v_exp_f32_e32 v107, v107
	v_rcp_f32_e32 v133, v98
	v_add_f32_e32 v98, 1.0, v105
	v_rcp_f32_e32 v140, v98
	v_add_f32_e32 v98, 1.0, v107
	v_rcp_f32_e32 v141, v98
	v_pk_mul_f32 v[64:65], v[116:117], v[64:65]
	v_pk_mul_f32 v[116:117], v[118:119], v[124:125]
	v_pk_mul_f32 v[66:67], v[66:67], v[132:133]
	v_pk_mul_f32 v[114:115], v[114:115], v[140:141]
	s_and_saveexec_b64 s[4:5], s[0:1]
	s_cbranch_execz .LBB0_148
	v_pk_mul_f32 v[118:119], v[64:65], v[64:65]
	v_pk_mul_f32 v[124:125], v[116:117], v[116:117]
	v_add_f32_e32 v98, v118, v119
	v_add_f32_e32 v98, v124, v98
	v_pk_mul_f32 v[132:133], v[66:67], v[66:67]
	v_add_f32_e32 v98, v125, v98
	v_add_f32_e32 v98, v132, v98
	v_pk_mul_f32 v[140:141], v[114:115], v[114:115]
	v_add_f32_e32 v98, v133, v98
	v_add_f32_e32 v98, v140, v98
	v_add_f32_e32 v98, v141, v98
	s_nop 1
	v_add_f32_dpp v98, v98, v98 row_ror:8 row_mask:0xf bank_mask:0xf bound_ctrl:1
	s_nop 1
	v_add_f32_dpp v98, v98, v98 row_ror:4 row_mask:0xf bank_mask:0xf bound_ctrl:1
	s_nop 1
	v_add_f32_dpp v98, v98, v98 row_ror:2 row_mask:0xf bank_mask:0xf bound_ctrl:1
	s_nop 1
	v_add_f32_dpp v98, v98, v98 row_ror:1 row_mask:0xf bank_mask:0xf bound_ctrl:1
	v_add_f32_e32 v98, 0x358637bd, v98
	v_mul_f32_e32 v105, 0x4b800000, v98
	v_cmp_gt_f32_e32 vcc, s29, v98
	s_nop 1
	v_cndmask_b32_e32 v98, v98, v105, vcc
	v_rsq_f32_e32 v98, v98
	s_nop 0
	v_mul_f32_e32 v105, 0x45800000, v98
	v_cndmask_b32_e32 v98, v98, v105, vcc
	v_mul_f32_e32 v98, v166, v98
	v_pk_mul_f32 v[64:65], v[64:65], v[98:99] op_sel_hi:[1,0]
	v_pk_mul_f32 v[116:117], v[116:117], v[98:99] op_sel_hi:[1,0]
	v_pk_mul_f32 v[66:67], v[66:67], v[98:99] op_sel_hi:[1,0]
	v_pk_mul_f32 v[114:115], v[114:115], v[98:99] op_sel_hi:[1,0]

; __device__ __forceinline__ void unpack8(const u32x4 w, float (&f)[8]) { f[0] = bf_lo(w.x); f[1] = bf_hi(w.x); f[2] = bf_lo(w.y); f[3] = bf_hi(w.y); f[4] = bf_lo(w.z); f[5] = bf_hi(w.z); f[6] = bf_lo(w.w); f[7] = bf_hi(w.w); }
; __device__ __forceinline__ float siluf_(float x) { return x * __builtin_amdgcn_rcpf(1.0f + __builtin_amdgcn_exp2f(x * -1.4426950408889634f)); }
; __device__ __forceinline__ void phase_qkv(const Args& a) {
;     ...
;         for (int m = 0; m < 16; ++m) {
;             float acc[8];
; #pragma unroll
;             for (int e = 0; e < 8; ++e) acc[e] = 0.f;
;             if (m == 0) { unpack8(R[0], F[0]); unpack8(R[1], F[1]); unpack8(R[2], F[2]); }
;             unpack8(R[m + 3], F[m + 3]);
; #pragma unroll
;             for (int i = 0; i < 4; ++i) {
;                 if (m + i < 3) { const float vm = (pos0 + m + i - 3 >= 0) ? 1.0f : 0.0f;
; #pragma unroll
;                     for (int e = 0; e < 8; ++e) acc[e] += F[m + i][e] * (w[i][e] * vm); }
;                 else {
; #pragma unroll
;                     for (int e = 0; e < 8; ++e) acc[e] += F[m + i][e] * w[i][e]; } }
;             float ssq = 0.f;
; #pragma unroll
;             for (int e = 0; e < 8; ++e) { acc[e] = siluf_(acc[e]); ssq += acc[e] * acc[e]; }
;             if (part < 2) { ssq = sum16(ssq); const float sc = rsqrtf(ssq + EPS) * qsc;
; #pragma unroll
;                 for (int e = 0; e < 8; ++e) acc[e] *= sc; }
.LBB0_150:
	s_or_b64 exec, exec, s[4:5]
	v_and_b32_e32 v119, 0xffff0000, v72
	v_lshlrev_b32_e32 v118, 16, v72
	v_and_b32_e32 v125, 0xffff0000, v73
	v_lshlrev_b32_e32 v124, 16, v73
	v_pk_fma_f32 v[72:73], v[22:23], v[146:147], 0 op_sel_hi:[1,1,0]
	v_pk_fma_f32 v[116:117], v[0:1], v[122:123], 0 op_sel_hi:[1,1,0]
	v_pk_fma_f32 v[72:73], v[26:27], v[144:145], v[72:73]
	v_and_b32_e32 v141, 0xffff0000, v75
	v_lshlrev_b32_e32 v140, 16, v75
	v_pk_fma_f32 v[72:73], v[30:31], v[142:143], v[72:73]
	v_pk_fma_f32 v[116:117], v[4:5], v[120:121], v[116:117]
	v_pk_fma_f32 v[114:115], v[34:35], v[140:141], v[72:73]
	v_pk_fma_f32 v[72:73], v[20:21], v[138:139], 0 op_sel_hi:[1,1,0]
	v_pk_fma_f32 v[116:117], v[12:13], v[112:113], v[116:117]
	v_pk_fma_f32 v[72:73], v[24:25], v[136:137], v[72:73]
	v_pk_fma_f32 v[116:117], v[8:9], v[118:119], v[116:117]
	v_and_b32_e32 v133, 0xffff0000, v74
	v_lshlrev_b32_e32 v132, 16, v74
	v_pk_fma_f32 v[72:73], v[28:29], v[134:135], v[72:73]
	v_mul_f32_e32 v98, 0xbfb8aa3b, v116
	v_pk_fma_f32 v[74:75], v[32:33], v[132:133], v[72:73]
	v_pk_fma_f32 v[72:73], v[2:3], v[130:131], 0 op_sel_hi:[1,1,0]
	v_exp_f32_e32 v98, v98
	v_mul_f32_e32 v105, 0xbfb8aa3b, v117
	v_pk_fma_f32 v[72:73], v[6:7], v[128:129], v[72:73]
	v_exp_f32_e32 v105, v105
	v_pk_fma_f32 v[72:73], v[14:15], v[126:127], v[72:73]
	v_mul_f32_e32 v107, 0xbfb8aa3b, v75
	v_pk_fma_f32 v[122:123], v[10:11], v[124:125], v[72:73]
	v_add_f32_e32 v72, 1.0, v98
	v_mul_f32_e32 v98, 0xbfb8aa3b, v122
	v_add_f32_e32 v73, 1.0, v105
	v_exp_f32_e32 v98, v98
	v_mul_f32_e32 v105, 0xbfb8aa3b, v123
	v_exp_f32_e32 v105, v105
	v_exp_f32_e32 v107, v107
	v_add_f32_e32 v98, 1.0, v98
	v_rcp_f32_e32 v130, v98
	v_add_f32_e32 v98, 1.0, v105
	v_mul_f32_e32 v105, 0xbfb8aa3b, v74
	v_exp_f32_e32 v105, v105
	v_rcp_f32_e32 v131, v98
	v_rcp_f32_e32 v72, v72
	v_rcp_f32_e32 v73, v73
	v_add_f32_e32 v98, 1.0, v105
	v_mul_f32_e32 v105, 0xbfb8aa3b, v114
	v_rcp_f32_e32 v138, v98
	v_add_f32_e32 v98, 1.0, v107
	v_exp_f32_e32 v105, v105
	v_mul_f32_e32 v107, 0xbfb8aa3b, v115
	v_exp_f32_e32 v107, v107
	v_rcp_f32_e32 v139, v98
	v_add_f32_e32 v98, 1.0, v105
	v_rcp_f32_e32 v146, v98
	v_add_f32_e32 v98, 1.0, v107
	v_rcp_f32_e32 v147, v98
	v_pk_mul_f32 v[72:73], v[116:117], v[72:73]
	v_pk_mul_f32 v[116:117], v[122:123], v[130:131]
	v_pk_mul_f32 v[74:75], v[74:75], v[138:139]
	v_pk_mul_f32 v[114:115], v[114:115], v[146:147]
	s_and_saveexec_b64 s[4:5], s[0:1]
	s_cbranch_execz .LBB0_152
	v_pk_mul_f32 v[122:123], v[72:73], v[72:73]
	v_pk_mul_f32 v[130:131], v[116:117], v[116:117]
	v_add_f32_e32 v98, v122, v123
	v_add_f32_e32 v98, v130, v98
	v_pk_mul_f32 v[138:139], v[74:75], v[74:75]
	v_add_f32_e32 v98, v131, v98
	v_add_f32_e32 v98, v138, v98
	v_pk_mul_f32 v[146:147], v[114:115], v[114:115]
	v_add_f32_e32 v98, v139, v98
	v_add_f32_e32 v98, v146, v98
	v_add_f32_e32 v98, v147, v98
	s_nop 1
	v_add_f32_dpp v98, v98, v98 row_ror:8 row_mask:0xf bank_mask:0xf bound_ctrl:1
	s_nop 1
	v_add_f32_dpp v98, v98, v98 row_ror:4 row_mask:0xf bank_mask:0xf bound_ctrl:1
	s_nop 1
	v_add_f32_dpp v98, v98, v98 row_ror:2 row_mask:0xf bank_mask:0xf bound_ctrl:1
	s_nop 1
	v_add_f32_dpp v98, v98, v98 row_ror:1 row_mask:0xf bank_mask:0xf bound_ctrl:1
	v_add_f32_e32 v98, 0x358637bd, v98
	v_mul_f32_e32 v105, 0x4b800000, v98
	v_cmp_gt_f32_e32 vcc, s29, v98
	s_nop 1
	v_cndmask_b32_e32 v98, v98, v105, vcc
	v_rsq_f32_e32 v98, v98
	s_nop 0
	v_mul_f32_e32 v105, 0x45800000, v98
	v_cndmask_b32_e32 v98, v98, v105, vcc
	v_mul_f32_e32 v98, v166, v98
	v_pk_mul_f32 v[72:73], v[72:73], v[98:99] op_sel_hi:[1,0]
	v_pk_mul_f32 v[116:117], v[116:117], v[98:99] op_sel_hi:[1,0]
	v_pk_mul_f32 v[74:75], v[74:75], v[98:99] op_sel_hi:[1,0]
	v_pk_mul_f32 v[114:115], v[114:115], v[98:99] op_sel_hi:[1,0]

; __device__ __forceinline__ void unpack8(const u32x4 w, float (&f)[8]) { f[0] = bf_lo(w.x); f[1] = bf_hi(w.x); f[2] = bf_lo(w.y); f[3] = bf_hi(w.y); f[4] = bf_lo(w.z); f[5] = bf_hi(w.z); f[6] = bf_lo(w.w); f[7] = bf_hi(w.w); }
; __device__ __forceinline__ float siluf_(float x) { return x * __builtin_amdgcn_rcpf(1.0f + __builtin_amdgcn_exp2f(x * -1.4426950408889634f)); }
; __device__ __forceinline__ void phase_qkv(const Args& a) {
;     ...
;         for (int m = 0; m < 16; ++m) {
;             float acc[8];
; #pragma unroll
;             for (int e = 0; e < 8; ++e) acc[e] = 0.f;
;             if (m == 0) { unpack8(R[0], F[0]); unpack8(R[1], F[1]); unpack8(R[2], F[2]); }
;             unpack8(R[m + 3], F[m + 3]);
; #pragma unroll
;             for (int i = 0; i < 4; ++i) {
;                 if (m + i < 3) { const float vm = (pos0 + m + i - 3 >= 0) ? 1.0f : 0.0f;
; #pragma unroll
;                     for (int e = 0; e < 8; ++e) acc[e] += F[m + i][e] * (w[i][e] * vm); }
;                 else {
; #pragma unroll
;                     for (int e = 0; e < 8; ++e) acc[e] += F[m + i][e] * w[i][e]; } }
;             float ssq = 0.f;
; #pragma unroll
;             for (int e = 0; e < 8; ++e) { acc[e] = siluf_(acc[e]); ssq += acc[e] * acc[e]; }
;             if (part < 2) { ssq = sum16(ssq); const float sc = rsqrtf(ssq + EPS) * qsc;
; #pragma unroll
;                 for (int e = 0; e < 8; ++e) acc[e] *= sc; }
.LBB0_154:
	s_or_b64 exec, exec, s[4:5]
	v_and_b32_e32 v117, 0xffff0000, v80
	v_lshlrev_b32_e32 v116, 16, v80
	v_and_b32_e32 v123, 0xffff0000, v81
	v_lshlrev_b32_e32 v122, 16, v81
	v_pk_fma_f32 v[80:81], v[22:23], v[144:145], 0 op_sel_hi:[1,1,0]
	v_pk_fma_f32 v[120:121], v[0:1], v[120:121], 0 op_sel_hi:[1,1,0]
	v_pk_fma_f32 v[80:81], v[26:27], v[142:143], v[80:81]
	v_and_b32_e32 v139, 0xffff0000, v83
	v_lshlrev_b32_e32 v138, 16, v83
	v_pk_fma_f32 v[80:81], v[30:31], v[140:141], v[80:81]
	v_pk_fma_f32 v[120:121], v[4:5], v[112:113], v[120:121]
	v_pk_fma_f32 v[114:115], v[34:35], v[138:139], v[80:81]
	v_pk_fma_f32 v[80:81], v[20:21], v[136:137], 0 op_sel_hi:[1,1,0]
	v_pk_fma_f32 v[120:121], v[12:13], v[118:119], v[120:121]
	v_pk_fma_f32 v[80:81], v[24:25], v[134:135], v[80:81]
	v_pk_fma_f32 v[120:121], v[8:9], v[116:117], v[120:121]
	v_and_b32_e32 v131, 0xffff0000, v82
	v_lshlrev_b32_e32 v130, 16, v82
	v_pk_fma_f32 v[80:81], v[28:29], v[132:133], v[80:81]
	v_mul_f32_e32 v98, 0xbfb8aa3b, v120
	v_pk_fma_f32 v[82:83], v[32:33], v[130:131], v[80:81]
	v_pk_fma_f32 v[80:81], v[2:3], v[128:129], 0 op_sel_hi:[1,1,0]
	v_exp_f32_e32 v98, v98
	v_mul_f32_e32 v105, 0xbfb8aa3b, v121
	v_pk_fma_f32 v[80:81], v[6:7], v[126:127], v[80:81]
	v_exp_f32_e32 v105, v105
	v_pk_fma_f32 v[80:81], v[14:15], v[124:125], v[80:81]
	v_mul_f32_e32 v107, 0xbfb8aa3b, v83
	v_pk_fma_f32 v[128:129], v[10:11], v[122:123], v[80:81]
	v_add_f32_e32 v80, 1.0, v98
	v_mul_f32_e32 v98, 0xbfb8aa3b, v128
	v_add_f32_e32 v81, 1.0, v105
	v_exp_f32_e32 v98, v98
	v_mul_f32_e32 v105, 0xbfb8aa3b, v129
	v_exp_f32_e32 v105, v105
	v_exp_f32_e32 v107, v107
	v_add_f32_e32 v98, 1.0, v98
	v_rcp_f32_e32 v136, v98
	v_add_f32_e32 v98, 1.0, v105
	v_mul_f32_e32 v105, 0xbfb8aa3b, v82
	v_exp_f32_e32 v105, v105
	v_rcp_f32_e32 v137, v98
	v_rcp_f32_e32 v80, v80
	v_rcp_f32_e32 v81, v81
	v_add_f32_e32 v98, 1.0, v105
	v_mul_f32_e32 v105, 0xbfb8aa3b, v114
	v_rcp_f32_e32 v144, v98
	v_add_f32_e32 v98, 1.0, v107
	v_exp_f32_e32 v105, v105
	v_mul_f32_e32 v107, 0xbfb8aa3b, v115
	v_exp_f32_e32 v107, v107
	v_rcp_f32_e32 v145, v98
	v_add_f32_e32 v98, 1.0, v105
	v_rcp_f32_e32 v146, v98
	v_add_f32_e32 v98, 1.0, v107
	v_rcp_f32_e32 v147, v98
	v_pk_mul_f32 v[80:81], v[120:121], v[80:81]
	v_pk_mul_f32 v[120:121], v[128:129], v[136:137]
	v_pk_mul_f32 v[82:83], v[82:83], v[144:145]
	v_pk_mul_f32 v[114:115], v[114:115], v[146:147]
	s_and_saveexec_b64 s[4:5], s[0:1]
	s_cbranch_execz .LBB0_156
	v_pk_mul_f32 v[128:129], v[80:81], v[80:81]
	v_pk_mul_f32 v[136:137], v[120:121], v[120:121]
	v_add_f32_e32 v98, v128, v129
	v_add_f32_e32 v98, v136, v98
	v_pk_mul_f32 v[144:145], v[82:83], v[82:83]
	v_add_f32_e32 v98, v137, v98
	v_add_f32_e32 v98, v144, v98
	v_pk_mul_f32 v[146:147], v[114:115], v[114:115]
	v_add_f32_e32 v98, v145, v98
	v_add_f32_e32 v98, v146, v98
	v_add_f32_e32 v98, v147, v98
	s_nop 1
	v_add_f32_dpp v98, v98, v98 row_ror:8 row_mask:0xf bank_mask:0xf bound_ctrl:1
	s_nop 1
	v_add_f32_dpp v98, v98, v98 row_ror:4 row_mask:0xf bank_mask:0xf bound_ctrl:1
	s_nop 1
	v_add_f32_dpp v98, v98, v98 row_ror:2 row_mask:0xf bank_mask:0xf bound_ctrl:1
	s_nop 1
	v_add_f32_dpp v98, v98, v98 row_ror:1 row_mask:0xf bank_mask:0xf bound_ctrl:1
	v_add_f32_e32 v98, 0x358637bd, v98
	v_mul_f32_e32 v105, 0x4b800000, v98
	v_cmp_gt_f32_e32 vcc, s29, v98
	s_nop 1
	v_cndmask_b32_e32 v98, v98, v105, vcc
	v_rsq_f32_e32 v98, v98
	s_nop 0
	v_mul_f32_e32 v105, 0x45800000, v98
	v_cndmask_b32_e32 v98, v98, v105, vcc
	v_mul_f32_e32 v98, v166, v98
	v_pk_mul_f32 v[80:81], v[80:81], v[98:99] op_sel_hi:[1,0]
	v_pk_mul_f32 v[120:121], v[120:121], v[98:99] op_sel_hi:[1,0]
	v_pk_mul_f32 v[82:83], v[82:83], v[98:99] op_sel_hi:[1,0]
	v_pk_mul_f32 v[114:115], v[114:115], v[98:99] op_sel_hi:[1,0]

; __device__ __forceinline__ void unpack8(const u32x4 w, float (&f)[8]) { f[0] = bf_lo(w.x); f[1] = bf_hi(w.x); f[2] = bf_lo(w.y); f[3] = bf_hi(w.y); f[4] = bf_lo(w.z); f[5] = bf_hi(w.z); f[6] = bf_lo(w.w); f[7] = bf_hi(w.w); }
; __device__ __forceinline__ float siluf_(float x) { return x * __builtin_amdgcn_rcpf(1.0f + __builtin_amdgcn_exp2f(x * -1.4426950408889634f)); }
; __device__ __forceinline__ void phase_qkv(const Args& a) {
;     ...
;         for (int m = 0; m < 16; ++m) {
;             float acc[8];
; #pragma unroll
;             for (int e = 0; e < 8; ++e) acc[e] = 0.f;
;             if (m == 0) { unpack8(R[0], F[0]); unpack8(R[1], F[1]); unpack8(R[2], F[2]); }
;             unpack8(R[m + 3], F[m + 3]);
; #pragma unroll
;             for (int i = 0; i < 4; ++i) {
;                 if (m + i < 3) { const float vm = (pos0 + m + i - 3 >= 0) ? 1.0f : 0.0f;
; #pragma unroll
;                     for (int e = 0; e < 8; ++e) acc[e] += F[m + i][e] * (w[i][e] * vm); }
;                 else {
; #pragma unroll
;                     for (int e = 0; e < 8; ++e) acc[e] += F[m + i][e] * w[i][e]; } }
;             float ssq = 0.f;
; #pragma unroll
;             for (int e = 0; e < 8; ++e) { acc[e] = siluf_(acc[e]); ssq += acc[e] * acc[e]; }
;             if (part < 2) { ssq = sum16(ssq); const float sc = rsqrtf(ssq + EPS) * qsc;
; #pragma unroll
;                 for (int e = 0; e < 8; ++e) acc[e] *= sc; }
.LBB0_158:
	s_or_b64 exec, exec, s[4:5]
	v_and_b32_e32 v115, 0xffff0000, v88
	v_lshlrev_b32_e32 v114, 16, v88
	v_and_b32_e32 v121, 0xffff0000, v89
	v_lshlrev_b32_e32 v120, 16, v89
	v_pk_fma_f32 v[88:89], v[22:23], v[142:143], 0 op_sel_hi:[1,1,0]
	v_pk_fma_f32 v[112:113], v[0:1], v[112:113], 0 op_sel_hi:[1,1,0]
	v_pk_fma_f32 v[88:89], v[26:27], v[140:141], v[88:89]
	v_and_b32_e32 v137, 0xffff0000, v91
	v_lshlrev_b32_e32 v136, 16, v91
	v_pk_fma_f32 v[88:89], v[30:31], v[138:139], v[88:89]
	v_pk_fma_f32 v[112:113], v[4:5], v[118:119], v[112:113]
	v_pk_fma_f32 v[142:143], v[34:35], v[136:137], v[88:89]
	v_pk_fma_f32 v[88:89], v[20:21], v[134:135], 0 op_sel_hi:[1,1,0]
	v_pk_fma_f32 v[112:113], v[12:13], v[116:117], v[112:113]
	v_pk_fma_f32 v[88:89], v[24:25], v[132:133], v[88:89]
	v_pk_fma_f32 v[112:113], v[8:9], v[114:115], v[112:113]
	v_and_b32_e32 v129, 0xffff0000, v90
	v_lshlrev_b32_e32 v128, 16, v90
	v_pk_fma_f32 v[88:89], v[28:29], v[130:131], v[88:89]
	v_mul_f32_e32 v98, 0xbfb8aa3b, v112
	v_pk_fma_f32 v[90:91], v[32:33], v[128:129], v[88:89]
	v_pk_fma_f32 v[88:89], v[2:3], v[126:127], 0 op_sel_hi:[1,1,0]
	v_exp_f32_e32 v98, v98
	v_mul_f32_e32 v105, 0xbfb8aa3b, v113
	v_pk_fma_f32 v[88:89], v[6:7], v[124:125], v[88:89]
	v_exp_f32_e32 v105, v105
	v_pk_fma_f32 v[88:89], v[14:15], v[122:123], v[88:89]
	v_mul_f32_e32 v107, 0xbfb8aa3b, v91
	v_pk_fma_f32 v[126:127], v[10:11], v[120:121], v[88:89]
	v_add_f32_e32 v88, 1.0, v98
	v_mul_f32_e32 v98, 0xbfb8aa3b, v126
	v_add_f32_e32 v89, 1.0, v105
	v_exp_f32_e32 v98, v98
	v_mul_f32_e32 v105, 0xbfb8aa3b, v127
	v_exp_f32_e32 v105, v105
	v_exp_f32_e32 v107, v107
	v_add_f32_e32 v98, 1.0, v98
	v_rcp_f32_e32 v134, v98
	v_add_f32_e32 v98, 1.0, v105
	v_mul_f32_e32 v105, 0xbfb8aa3b, v90
	v_exp_f32_e32 v105, v105
	v_rcp_f32_e32 v135, v98
	v_rcp_f32_e32 v88, v88
	v_rcp_f32_e32 v89, v89
	v_add_f32_e32 v98, 1.0, v105
	v_mul_f32_e32 v105, 0xbfb8aa3b, v142
	v_rcp_f32_e32 v144, v98
	v_add_f32_e32 v98, 1.0, v107
	v_exp_f32_e32 v105, v105
	v_mul_f32_e32 v107, 0xbfb8aa3b, v143
	v_exp_f32_e32 v107, v107
	v_rcp_f32_e32 v145, v98
	v_add_f32_e32 v98, 1.0, v105
	v_rcp_f32_e32 v146, v98
	v_add_f32_e32 v98, 1.0, v107
	v_rcp_f32_e32 v147, v98
	v_pk_mul_f32 v[88:89], v[112:113], v[88:89]
	v_pk_mul_f32 v[126:127], v[126:127], v[134:135]
	v_pk_mul_f32 v[90:91], v[90:91], v[144:145]
	v_pk_mul_f32 v[112:113], v[142:143], v[146:147]
	s_and_saveexec_b64 s[4:5], s[0:1]
	s_cbranch_execz .LBB0_160
	v_pk_mul_f32 v[134:135], v[88:89], v[88:89]
	v_pk_mul_f32 v[142:143], v[126:127], v[126:127]
	v_add_f32_e32 v98, v134, v135
	v_add_f32_e32 v98, v142, v98
	v_pk_mul_f32 v[144:145], v[90:91], v[90:91]
	v_add_f32_e32 v98, v143, v98
	v_add_f32_e32 v98, v144, v98
	v_pk_mul_f32 v[146:147], v[112:113], v[112:113]
	v_add_f32_e32 v98, v145, v98
	v_add_f32_e32 v98, v146, v98
	v_add_f32_e32 v98, v147, v98
	s_nop 1
	v_add_f32_dpp v98, v98, v98 row_ror:8 row_mask:0xf bank_mask:0xf bound_ctrl:1
	s_nop 1
	v_add_f32_dpp v98, v98, v98 row_ror:4 row_mask:0xf bank_mask:0xf bound_ctrl:1
	s_nop 1
	v_add_f32_dpp v98, v98, v98 row_ror:2 row_mask:0xf bank_mask:0xf bound_ctrl:1
	s_nop 1
	v_add_f32_dpp v98, v98, v98 row_ror:1 row_mask:0xf bank_mask:0xf bound_ctrl:1
	v_add_f32_e32 v98, 0x358637bd, v98
	v_mul_f32_e32 v105, 0x4b800000, v98
	v_cmp_gt_f32_e32 vcc, s29, v98
	s_nop 1
	v_cndmask_b32_e32 v98, v98, v105, vcc
	v_rsq_f32_e32 v98, v98
	s_nop 0
	v_mul_f32_e32 v105, 0x45800000, v98
	v_cndmask_b32_e32 v98, v98, v105, vcc
	v_mul_f32_e32 v98, v166, v98
	v_pk_mul_f32 v[88:89], v[88:89], v[98:99] op_sel_hi:[1,0]
	v_pk_mul_f32 v[126:127], v[126:127], v[98:99] op_sel_hi:[1,0]
	v_pk_mul_f32 v[90:91], v[90:91], v[98:99] op_sel_hi:[1,0]
	v_pk_mul_f32 v[112:113], v[112:113], v[98:99] op_sel_hi:[1,0]

; __device__ __forceinline__ void unpack8(const u32x4 w, float (&f)[8]) { f[0] = bf_lo(w.x); f[1] = bf_hi(w.x); f[2] = bf_lo(w.y); f[3] = bf_hi(w.y); f[4] = bf_lo(w.z); f[5] = bf_hi(w.z); f[6] = bf_lo(w.w); f[7] = bf_hi(w.w); }
; __device__ __forceinline__ float siluf_(float x) { return x * __builtin_amdgcn_rcpf(1.0f + __builtin_amdgcn_exp2f(x * -1.4426950408889634f)); }
; __device__ __forceinline__ void phase_qkv(const Args& a) {
;     ...
;         for (int m = 0; m < 16; ++m) {
;             float acc[8];
; #pragma unroll
;             for (int e = 0; e < 8; ++e) acc[e] = 0.f;
;             if (m == 0) { unpack8(R[0], F[0]); unpack8(R[1], F[1]); unpack8(R[2], F[2]); }
;             unpack8(R[m + 3], F[m + 3]);
; #pragma unroll
;             for (int i = 0; i < 4; ++i) {
;                 if (m + i < 3) { const float vm = (pos0 + m + i - 3 >= 0) ? 1.0f : 0.0f;
; #pragma unroll
;                     for (int e = 0; e < 8; ++e) acc[e] += F[m + i][e] * (w[i][e] * vm); }
;                 else {
; #pragma unroll
;                     for (int e = 0; e < 8; ++e) acc[e] += F[m + i][e] * w[i][e]; } }
;             float ssq = 0.f;
; #pragma unroll
;             for (int e = 0; e < 8; ++e) { acc[e] = siluf_(acc[e]); ssq += acc[e] * acc[e]; }
;             if (part < 2) { ssq = sum16(ssq); const float sc = rsqrtf(ssq + EPS) * qsc;
; #pragma unroll
;                 for (int e = 0; e < 8; ++e) acc[e] *= sc; }
.LBB0_162:
	s_or_b64 exec, exec, s[4:5]
	v_and_b32_e32 v113, 0xffff0000, v92
	v_lshlrev_b32_e32 v112, 16, v92
	v_and_b32_e32 v127, 0xffff0000, v93
	v_lshlrev_b32_e32 v126, 16, v93
	v_pk_fma_f32 v[92:93], v[22:23], v[140:141], 0 op_sel_hi:[1,1,0]
	v_pk_fma_f32 v[118:119], v[0:1], v[118:119], 0 op_sel_hi:[1,1,0]
	v_pk_fma_f32 v[92:93], v[26:27], v[138:139], v[92:93]
	v_and_b32_e32 v143, 0xffff0000, v95
	v_lshlrev_b32_e32 v142, 16, v95
	v_pk_fma_f32 v[92:93], v[30:31], v[136:137], v[92:93]
	v_pk_fma_f32 v[118:119], v[4:5], v[116:117], v[118:119]
	v_pk_fma_f32 v[140:141], v[34:35], v[142:143], v[92:93]
	v_pk_fma_f32 v[92:93], v[20:21], v[132:133], 0 op_sel_hi:[1,1,0]
	v_pk_fma_f32 v[118:119], v[12:13], v[114:115], v[118:119]
	v_pk_fma_f32 v[92:93], v[24:25], v[130:131], v[92:93]
	v_pk_fma_f32 v[118:119], v[8:9], v[112:113], v[118:119]
	v_and_b32_e32 v135, 0xffff0000, v94
	v_lshlrev_b32_e32 v134, 16, v94
	v_pk_fma_f32 v[92:93], v[28:29], v[128:129], v[92:93]
	v_mul_f32_e32 v98, 0xbfb8aa3b, v118
	v_pk_fma_f32 v[94:95], v[32:33], v[134:135], v[92:93]
	v_pk_fma_f32 v[92:93], v[2:3], v[124:125], 0 op_sel_hi:[1,1,0]
	v_exp_f32_e32 v98, v98
	v_mul_f32_e32 v105, 0xbfb8aa3b, v119
	v_pk_fma_f32 v[92:93], v[6:7], v[122:123], v[92:93]
	v_exp_f32_e32 v105, v105
	v_pk_fma_f32 v[92:93], v[14:15], v[120:121], v[92:93]
	v_mul_f32_e32 v107, 0xbfb8aa3b, v95
	v_pk_fma_f32 v[124:125], v[10:11], v[126:127], v[92:93]
	v_add_f32_e32 v92, 1.0, v98
	v_mul_f32_e32 v98, 0xbfb8aa3b, v124
	v_add_f32_e32 v93, 1.0, v105
	v_exp_f32_e32 v98, v98
	v_mul_f32_e32 v105, 0xbfb8aa3b, v125
	v_exp_f32_e32 v105, v105
	v_exp_f32_e32 v107, v107
	v_add_f32_e32 v98, 1.0, v98
	v_rcp_f32_e32 v132, v98
	v_add_f32_e32 v98, 1.0, v105
	v_mul_f32_e32 v105, 0xbfb8aa3b, v94
	v_exp_f32_e32 v105, v105
	v_rcp_f32_e32 v133, v98
	v_rcp_f32_e32 v92, v92
	v_rcp_f32_e32 v93, v93
	v_add_f32_e32 v98, 1.0, v105
	v_mul_f32_e32 v105, 0xbfb8aa3b, v140
	v_rcp_f32_e32 v144, v98
	v_add_f32_e32 v98, 1.0, v107
	v_exp_f32_e32 v105, v105
	v_mul_f32_e32 v107, 0xbfb8aa3b, v141
	v_exp_f32_e32 v107, v107
	v_rcp_f32_e32 v145, v98
	v_add_f32_e32 v98, 1.0, v105
	v_rcp_f32_e32 v146, v98
	v_add_f32_e32 v98, 1.0, v107
	v_rcp_f32_e32 v147, v98
	v_pk_mul_f32 v[92:93], v[118:119], v[92:93]
	v_pk_mul_f32 v[124:125], v[124:125], v[132:133]
	v_pk_mul_f32 v[94:95], v[94:95], v[144:145]
	v_pk_mul_f32 v[118:119], v[140:141], v[146:147]
	s_and_saveexec_b64 s[4:5], s[0:1]
	s_cbranch_execz .LBB0_164
	v_pk_mul_f32 v[132:133], v[92:93], v[92:93]
	v_pk_mul_f32 v[140:141], v[124:125], v[124:125]
	v_add_f32_e32 v98, v132, v133
	v_add_f32_e32 v98, v140, v98
	v_pk_mul_f32 v[144:145], v[94:95], v[94:95]
	v_add_f32_e32 v98, v141, v98
	v_add_f32_e32 v98, v144, v98
	v_pk_mul_f32 v[146:147], v[118:119], v[118:119]
	v_add_f32_e32 v98, v145, v98
	v_add_f32_e32 v98, v146, v98
	v_add_f32_e32 v98, v147, v98
	s_nop 1
	v_add_f32_dpp v98, v98, v98 row_ror:8 row_mask:0xf bank_mask:0xf bound_ctrl:1
	s_nop 1
	v_add_f32_dpp v98, v98, v98 row_ror:4 row_mask:0xf bank_mask:0xf bound_ctrl:1
	s_nop 1
	v_add_f32_dpp v98, v98, v98 row_ror:2 row_mask:0xf bank_mask:0xf bound_ctrl:1
	s_nop 1
	v_add_f32_dpp v98, v98, v98 row_ror:1 row_mask:0xf bank_mask:0xf bound_ctrl:1
	v_add_f32_e32 v98, 0x358637bd, v98
	v_mul_f32_e32 v105, 0x4b800000, v98
	v_cmp_gt_f32_e32 vcc, s29, v98
	s_nop 1
	v_cndmask_b32_e32 v98, v98, v105, vcc
	v_rsq_f32_e32 v98, v98
	s_nop 0
	v_mul_f32_e32 v105, 0x45800000, v98
	v_cndmask_b32_e32 v98, v98, v105, vcc
	v_mul_f32_e32 v98, v166, v98
	v_pk_mul_f32 v[92:93], v[92:93], v[98:99] op_sel_hi:[1,0]
	v_pk_mul_f32 v[124:125], v[124:125], v[98:99] op_sel_hi:[1,0]
	v_pk_mul_f32 v[94:95], v[94:95], v[98:99] op_sel_hi:[1,0]
	v_pk_mul_f32 v[118:119], v[118:119], v[98:99] op_sel_hi:[1,0]

; __device__ __forceinline__ void unpack8(const u32x4 w, float (&f)[8]) { f[0] = bf_lo(w.x); f[1] = bf_hi(w.x); f[2] = bf_lo(w.y); f[3] = bf_hi(w.y); f[4] = bf_lo(w.z); f[5] = bf_hi(w.z); f[6] = bf_lo(w.w); f[7] = bf_hi(w.w); }
; __device__ __forceinline__ float siluf_(float x) { return x * __builtin_amdgcn_rcpf(1.0f + __builtin_amdgcn_exp2f(x * -1.4426950408889634f)); }
; __device__ __forceinline__ void phase_qkv(const Args& a) {
;     ...
;         for (int m = 0; m < 16; ++m) {
;             float acc[8];
; #pragma unroll
;             for (int e = 0; e < 8; ++e) acc[e] = 0.f;
;             if (m == 0) { unpack8(R[0], F[0]); unpack8(R[1], F[1]); unpack8(R[2], F[2]); }
;             unpack8(R[m + 3], F[m + 3]);
; #pragma unroll
;             for (int i = 0; i < 4; ++i) {
;                 if (m + i < 3) { const float vm = (pos0 + m + i - 3 >= 0) ? 1.0f : 0.0f;
; #pragma unroll
;                     for (int e = 0; e < 8; ++e) acc[e] += F[m + i][e] * (w[i][e] * vm); }
;                 else {
; #pragma unroll
;                     for (int e = 0; e < 8; ++e) acc[e] += F[m + i][e] * w[i][e]; } }
;             float ssq = 0.f;
; #pragma unroll
;             for (int e = 0; e < 8; ++e) { acc[e] = siluf_(acc[e]); ssq += acc[e] * acc[e]; }
;             if (part < 2) { ssq = sum16(ssq); const float sc = rsqrtf(ssq + EPS) * qsc;
; #pragma unroll
;                 for (int e = 0; e < 8; ++e) acc[e] *= sc; }
.LBB0_166:
	s_or_b64 exec, exec, s[4:5]
	v_and_b32_e32 v119, 0xffff0000, v84
	v_lshlrev_b32_e32 v118, 16, v84
	v_and_b32_e32 v125, 0xffff0000, v85
	v_lshlrev_b32_e32 v124, 16, v85
	v_pk_fma_f32 v[84:85], v[22:23], v[138:139], 0 op_sel_hi:[1,1,0]
	v_pk_fma_f32 v[116:117], v[0:1], v[116:117], 0 op_sel_hi:[1,1,0]
	v_pk_fma_f32 v[84:85], v[26:27], v[136:137], v[84:85]
	v_and_b32_e32 v141, 0xffff0000, v87
	v_lshlrev_b32_e32 v140, 16, v87
	v_pk_fma_f32 v[84:85], v[30:31], v[142:143], v[84:85]
	v_pk_fma_f32 v[116:117], v[4:5], v[114:115], v[116:117]
	v_pk_fma_f32 v[138:139], v[34:35], v[140:141], v[84:85]
	v_pk_fma_f32 v[84:85], v[20:21], v[130:131], 0 op_sel_hi:[1,1,0]
	v_pk_fma_f32 v[116:117], v[12:13], v[112:113], v[116:117]
	v_pk_fma_f32 v[84:85], v[24:25], v[128:129], v[84:85]
	v_pk_fma_f32 v[116:117], v[8:9], v[118:119], v[116:117]
	v_and_b32_e32 v133, 0xffff0000, v86
	v_lshlrev_b32_e32 v132, 16, v86
	v_pk_fma_f32 v[84:85], v[28:29], v[134:135], v[84:85]
	v_mul_f32_e32 v98, 0xbfb8aa3b, v116
	v_pk_fma_f32 v[86:87], v[32:33], v[132:133], v[84:85]
	v_pk_fma_f32 v[84:85], v[2:3], v[122:123], 0 op_sel_hi:[1,1,0]
	v_exp_f32_e32 v98, v98
	v_mul_f32_e32 v105, 0xbfb8aa3b, v117
	v_pk_fma_f32 v[84:85], v[6:7], v[120:121], v[84:85]
	v_exp_f32_e32 v105, v105
	v_pk_fma_f32 v[84:85], v[14:15], v[126:127], v[84:85]
	v_mul_f32_e32 v107, 0xbfb8aa3b, v87
	v_pk_fma_f32 v[122:123], v[10:11], v[124:125], v[84:85]
	v_add_f32_e32 v84, 1.0, v98
	v_mul_f32_e32 v98, 0xbfb8aa3b, v122
	v_add_f32_e32 v85, 1.0, v105
	v_exp_f32_e32 v98, v98
	v_mul_f32_e32 v105, 0xbfb8aa3b, v123
	v_exp_f32_e32 v105, v105
	v_exp_f32_e32 v107, v107
	v_add_f32_e32 v98, 1.0, v98
	v_rcp_f32_e32 v130, v98
	v_add_f32_e32 v98, 1.0, v105
	v_mul_f32_e32 v105, 0xbfb8aa3b, v86
	v_exp_f32_e32 v105, v105
	v_rcp_f32_e32 v131, v98
	v_rcp_f32_e32 v84, v84
	v_rcp_f32_e32 v85, v85
	v_add_f32_e32 v98, 1.0, v105
	v_mul_f32_e32 v105, 0xbfb8aa3b, v138
	v_rcp_f32_e32 v144, v98
	v_add_f32_e32 v98, 1.0, v107
	v_exp_f32_e32 v105, v105
	v_mul_f32_e32 v107, 0xbfb8aa3b, v139
	v_exp_f32_e32 v107, v107
	v_rcp_f32_e32 v145, v98
	v_add_f32_e32 v98, 1.0, v105
	v_rcp_f32_e32 v146, v98
	v_add_f32_e32 v98, 1.0, v107
	v_rcp_f32_e32 v147, v98
	v_pk_mul_f32 v[84:85], v[116:117], v[84:85]
	v_pk_mul_f32 v[122:123], v[122:123], v[130:131]
	v_pk_mul_f32 v[86:87], v[86:87], v[144:145]
	v_pk_mul_f32 v[116:117], v[138:139], v[146:147]
	s_and_saveexec_b64 s[4:5], s[0:1]
	s_cbranch_execz .LBB0_168
	v_pk_mul_f32 v[130:131], v[84:85], v[84:85]
	v_pk_mul_f32 v[138:139], v[122:123], v[122:123]
	v_add_f32_e32 v98, v130, v131
	v_add_f32_e32 v98, v138, v98
	v_pk_mul_f32 v[144:145], v[86:87], v[86:87]
	v_add_f32_e32 v98, v139, v98
	v_add_f32_e32 v98, v144, v98
	v_pk_mul_f32 v[146:147], v[116:117], v[116:117]
	v_add_f32_e32 v98, v145, v98
	v_add_f32_e32 v98, v146, v98
	v_add_f32_e32 v98, v147, v98
	s_nop 1
	v_add_f32_dpp v98, v98, v98 row_ror:8 row_mask:0xf bank_mask:0xf bound_ctrl:1
	s_nop 1
	v_add_f32_dpp v98, v98, v98 row_ror:4 row_mask:0xf bank_mask:0xf bound_ctrl:1
	s_nop 1
	v_add_f32_dpp v98, v98, v98 row_ror:2 row_mask:0xf bank_mask:0xf bound_ctrl:1
	s_nop 1
	v_add_f32_dpp v98, v98, v98 row_ror:1 row_mask:0xf bank_mask:0xf bound_ctrl:1
	v_add_f32_e32 v98, 0x358637bd, v98
	v_mul_f32_e32 v105, 0x4b800000, v98
	v_cmp_gt_f32_e32 vcc, s29, v98
	s_nop 1
	v_cndmask_b32_e32 v98, v98, v105, vcc
	v_rsq_f32_e32 v98, v98
	s_nop 0
	v_mul_f32_e32 v105, 0x45800000, v98
	v_cndmask_b32_e32 v98, v98, v105, vcc
	v_mul_f32_e32 v98, v166, v98
	v_pk_mul_f32 v[84:85], v[84:85], v[98:99] op_sel_hi:[1,0]
	v_pk_mul_f32 v[122:123], v[122:123], v[98:99] op_sel_hi:[1,0]
	v_pk_mul_f32 v[86:87], v[86:87], v[98:99] op_sel_hi:[1,0]
	v_pk_mul_f32 v[116:117], v[116:117], v[98:99] op_sel_hi:[1,0]

; __device__ __forceinline__ void unpack8(const u32x4 w, float (&f)[8]) { f[0] = bf_lo(w.x); f[1] = bf_hi(w.x); f[2] = bf_lo(w.y); f[3] = bf_hi(w.y); f[4] = bf_lo(w.z); f[5] = bf_hi(w.z); f[6] = bf_lo(w.w); f[7] = bf_hi(w.w); }
; __device__ __forceinline__ float siluf_(float x) { return x * __builtin_amdgcn_rcpf(1.0f + __builtin_amdgcn_exp2f(x * -1.4426950408889634f)); }
; __device__ __forceinline__ void phase_qkv(const Args& a) {
;     ...
;         for (int m = 0; m < 16; ++m) {
;             float acc[8];
; #pragma unroll
;             for (int e = 0; e < 8; ++e) acc[e] = 0.f;
;             if (m == 0) { unpack8(R[0], F[0]); unpack8(R[1], F[1]); unpack8(R[2], F[2]); }
;             unpack8(R[m + 3], F[m + 3]);
; #pragma unroll
;             for (int i = 0; i < 4; ++i) {
;                 if (m + i < 3) { const float vm = (pos0 + m + i - 3 >= 0) ? 1.0f : 0.0f;
; #pragma unroll
;                     for (int e = 0; e < 8; ++e) acc[e] += F[m + i][e] * (w[i][e] * vm); }
;                 else {
; #pragma unroll
;                     for (int e = 0; e < 8; ++e) acc[e] += F[m + i][e] * w[i][e]; } }
;             float ssq = 0.f;
; #pragma unroll
;             for (int e = 0; e < 8; ++e) { acc[e] = siluf_(acc[e]); ssq += acc[e] * acc[e]; }
;             if (part < 2) { ssq = sum16(ssq); const float sc = rsqrtf(ssq + EPS) * qsc;
; #pragma unroll
;                 for (int e = 0; e < 8; ++e) acc[e] *= sc; }
.LBB0_170:
	s_or_b64 exec, exec, s[4:5]
	v_and_b32_e32 v117, 0xffff0000, v76
	v_lshlrev_b32_e32 v116, 16, v76
	v_and_b32_e32 v123, 0xffff0000, v77
	v_lshlrev_b32_e32 v122, 16, v77
	v_pk_fma_f32 v[76:77], v[22:23], v[136:137], 0 op_sel_hi:[1,1,0]
	v_pk_fma_f32 v[114:115], v[0:1], v[114:115], 0 op_sel_hi:[1,1,0]
	v_pk_fma_f32 v[76:77], v[26:27], v[142:143], v[76:77]
	v_and_b32_e32 v139, 0xffff0000, v79
	v_lshlrev_b32_e32 v138, 16, v79
	v_pk_fma_f32 v[76:77], v[30:31], v[140:141], v[76:77]
	v_pk_fma_f32 v[114:115], v[4:5], v[112:113], v[114:115]
	v_pk_fma_f32 v[136:137], v[34:35], v[138:139], v[76:77]
	v_pk_fma_f32 v[76:77], v[20:21], v[128:129], 0 op_sel_hi:[1,1,0]
	v_pk_fma_f32 v[114:115], v[12:13], v[118:119], v[114:115]
	v_pk_fma_f32 v[76:77], v[24:25], v[134:135], v[76:77]
	v_pk_fma_f32 v[114:115], v[8:9], v[116:117], v[114:115]
	v_and_b32_e32 v131, 0xffff0000, v78
	v_lshlrev_b32_e32 v130, 16, v78
	v_pk_fma_f32 v[76:77], v[28:29], v[132:133], v[76:77]
	v_mul_f32_e32 v98, 0xbfb8aa3b, v114
	v_pk_fma_f32 v[78:79], v[32:33], v[130:131], v[76:77]
	v_pk_fma_f32 v[76:77], v[2:3], v[120:121], 0 op_sel_hi:[1,1,0]
	v_exp_f32_e32 v98, v98
	v_mul_f32_e32 v105, 0xbfb8aa3b, v115
	v_pk_fma_f32 v[76:77], v[6:7], v[126:127], v[76:77]
	v_exp_f32_e32 v105, v105
	v_pk_fma_f32 v[76:77], v[14:15], v[124:125], v[76:77]
	v_mul_f32_e32 v107, 0xbfb8aa3b, v79
	v_pk_fma_f32 v[120:121], v[10:11], v[122:123], v[76:77]
	v_add_f32_e32 v76, 1.0, v98
	v_mul_f32_e32 v98, 0xbfb8aa3b, v120
	v_add_f32_e32 v77, 1.0, v105
	v_exp_f32_e32 v98, v98
	v_mul_f32_e32 v105, 0xbfb8aa3b, v121
	v_exp_f32_e32 v105, v105
	v_exp_f32_e32 v107, v107
	v_add_f32_e32 v98, 1.0, v98
	v_rcp_f32_e32 v128, v98
	v_add_f32_e32 v98, 1.0, v105
	v_mul_f32_e32 v105, 0xbfb8aa3b, v78
	v_exp_f32_e32 v105, v105
	v_rcp_f32_e32 v129, v98
	v_rcp_f32_e32 v76, v76
	v_rcp_f32_e32 v77, v77
	v_add_f32_e32 v98, 1.0, v105
	v_mul_f32_e32 v105, 0xbfb8aa3b, v136
	v_rcp_f32_e32 v144, v98
	v_add_f32_e32 v98, 1.0, v107
	v_exp_f32_e32 v105, v105
	v_mul_f32_e32 v107, 0xbfb8aa3b, v137
	v_exp_f32_e32 v107, v107
	v_rcp_f32_e32 v145, v98
	v_add_f32_e32 v98, 1.0, v105
	v_rcp_f32_e32 v146, v98
	v_add_f32_e32 v98, 1.0, v107
	v_rcp_f32_e32 v147, v98
	v_pk_mul_f32 v[76:77], v[114:115], v[76:77]
	v_pk_mul_f32 v[120:121], v[120:121], v[128:129]
	v_pk_mul_f32 v[78:79], v[78:79], v[144:145]
	v_pk_mul_f32 v[114:115], v[136:137], v[146:147]
	s_and_saveexec_b64 s[4:5], s[0:1]
	s_cbranch_execz .LBB0_172
	v_pk_mul_f32 v[128:129], v[76:77], v[76:77]
	v_pk_mul_f32 v[136:137], v[120:121], v[120:121]
	v_add_f32_e32 v98, v128, v129
	v_add_f32_e32 v98, v136, v98
	v_pk_mul_f32 v[144:145], v[78:79], v[78:79]
	v_add_f32_e32 v98, v137, v98
	v_add_f32_e32 v98, v144, v98
	v_pk_mul_f32 v[146:147], v[114:115], v[114:115]
	v_add_f32_e32 v98, v145, v98
	v_add_f32_e32 v98, v146, v98
	v_add_f32_e32 v98, v147, v98
	s_nop 1
	v_add_f32_dpp v98, v98, v98 row_ror:8 row_mask:0xf bank_mask:0xf bound_ctrl:1
	s_nop 1
	v_add_f32_dpp v98, v98, v98 row_ror:4 row_mask:0xf bank_mask:0xf bound_ctrl:1
	s_nop 1
	v_add_f32_dpp v98, v98, v98 row_ror:2 row_mask:0xf bank_mask:0xf bound_ctrl:1
	s_nop 1
	v_add_f32_dpp v98, v98, v98 row_ror:1 row_mask:0xf bank_mask:0xf bound_ctrl:1
	v_add_f32_e32 v98, 0x358637bd, v98
	v_mul_f32_e32 v105, 0x4b800000, v98
	v_cmp_gt_f32_e32 vcc, s29, v98
	s_nop 1
	v_cndmask_b32_e32 v98, v98, v105, vcc
	v_rsq_f32_e32 v98, v98
	s_nop 0
	v_mul_f32_e32 v105, 0x45800000, v98
	v_cndmask_b32_e32 v98, v98, v105, vcc
	v_mul_f32_e32 v98, v166, v98
	v_pk_mul_f32 v[76:77], v[76:77], v[98:99] op_sel_hi:[1,0]
	v_pk_mul_f32 v[120:121], v[120:121], v[98:99] op_sel_hi:[1,0]
	v_pk_mul_f32 v[78:79], v[78:79], v[98:99] op_sel_hi:[1,0]
	v_pk_mul_f32 v[114:115], v[114:115], v[98:99] op_sel_hi:[1,0]

; __device__ __forceinline__ void unpack8(const u32x4 w, float (&f)[8]) { f[0] = bf_lo(w.x); f[1] = bf_hi(w.x); f[2] = bf_lo(w.y); f[3] = bf_hi(w.y); f[4] = bf_lo(w.z); f[5] = bf_hi(w.z); f[6] = bf_lo(w.w); f[7] = bf_hi(w.w); }
; __device__ __forceinline__ float siluf_(float x) { return x * __builtin_amdgcn_rcpf(1.0f + __builtin_amdgcn_exp2f(x * -1.4426950408889634f)); }
; __device__ __forceinline__ void phase_qkv(const Args& a) {
;     ...
;         for (int m = 0; m < 16; ++m) {
;             float acc[8];
; #pragma unroll
;             for (int e = 0; e < 8; ++e) acc[e] = 0.f;
;             if (m == 0) { unpack8(R[0], F[0]); unpack8(R[1], F[1]); unpack8(R[2], F[2]); }
;             unpack8(R[m + 3], F[m + 3]);
; #pragma unroll
;             for (int i = 0; i < 4; ++i) {
;                 if (m + i < 3) { const float vm = (pos0 + m + i - 3 >= 0) ? 1.0f : 0.0f;
; #pragma unroll
;                     for (int e = 0; e < 8; ++e) acc[e] += F[m + i][e] * (w[i][e] * vm); }
;                 else {
; #pragma unroll
;                     for (int e = 0; e < 8; ++e) acc[e] += F[m + i][e] * w[i][e]; } }
;             float ssq = 0.f;
; #pragma unroll
;             for (int e = 0; e < 8; ++e) { acc[e] = siluf_(acc[e]); ssq += acc[e] * acc[e]; }
;             if (part < 2) { ssq = sum16(ssq); const float sc = rsqrtf(ssq + EPS) * qsc;
; #pragma unroll
;                 for (int e = 0; e < 8; ++e) acc[e] *= sc; }
.LBB0_174:
	s_or_b64 exec, exec, s[4:5]
	v_and_b32_e32 v115, 0xffff0000, v68
	v_lshlrev_b32_e32 v114, 16, v68
	v_and_b32_e32 v121, 0xffff0000, v69
	v_lshlrev_b32_e32 v120, 16, v69
	v_pk_fma_f32 v[68:69], v[22:23], v[142:143], 0 op_sel_hi:[1,1,0]
	v_pk_fma_f32 v[112:113], v[0:1], v[112:113], 0 op_sel_hi:[1,1,0]
	v_pk_fma_f32 v[68:69], v[26:27], v[140:141], v[68:69]
	v_and_b32_e32 v137, 0xffff0000, v71
	v_lshlrev_b32_e32 v136, 16, v71
	v_pk_fma_f32 v[68:69], v[30:31], v[138:139], v[68:69]
	v_pk_fma_f32 v[112:113], v[4:5], v[118:119], v[112:113]
	v_pk_fma_f32 v[142:143], v[34:35], v[136:137], v[68:69]
	v_pk_fma_f32 v[68:69], v[20:21], v[134:135], 0 op_sel_hi:[1,1,0]
	v_pk_fma_f32 v[112:113], v[12:13], v[116:117], v[112:113]
	v_pk_fma_f32 v[68:69], v[24:25], v[132:133], v[68:69]
	v_pk_fma_f32 v[112:113], v[8:9], v[114:115], v[112:113]
	v_and_b32_e32 v129, 0xffff0000, v70
	v_lshlrev_b32_e32 v128, 16, v70
	v_pk_fma_f32 v[68:69], v[28:29], v[130:131], v[68:69]
	v_mul_f32_e32 v98, 0xbfb8aa3b, v112
	v_pk_fma_f32 v[70:71], v[32:33], v[128:129], v[68:69]
	v_pk_fma_f32 v[68:69], v[2:3], v[126:127], 0 op_sel_hi:[1,1,0]
	v_exp_f32_e32 v98, v98
	v_mul_f32_e32 v105, 0xbfb8aa3b, v113
	v_pk_fma_f32 v[68:69], v[6:7], v[124:125], v[68:69]
	v_exp_f32_e32 v105, v105
	v_pk_fma_f32 v[68:69], v[14:15], v[122:123], v[68:69]
	v_mul_f32_e32 v107, 0xbfb8aa3b, v71
	v_pk_fma_f32 v[126:127], v[10:11], v[120:121], v[68:69]
	v_add_f32_e32 v68, 1.0, v98
	v_mul_f32_e32 v98, 0xbfb8aa3b, v126
	v_add_f32_e32 v69, 1.0, v105
	v_exp_f32_e32 v98, v98
	v_mul_f32_e32 v105, 0xbfb8aa3b, v127
	v_exp_f32_e32 v105, v105
	v_exp_f32_e32 v107, v107
	v_add_f32_e32 v98, 1.0, v98
	v_rcp_f32_e32 v134, v98
	v_add_f32_e32 v98, 1.0, v105
	v_mul_f32_e32 v105, 0xbfb8aa3b, v70
	v_exp_f32_e32 v105, v105
	v_rcp_f32_e32 v135, v98
	v_rcp_f32_e32 v68, v68
	v_rcp_f32_e32 v69, v69
	v_add_f32_e32 v98, 1.0, v105
	v_mul_f32_e32 v105, 0xbfb8aa3b, v142
	v_rcp_f32_e32 v144, v98
	v_add_f32_e32 v98, 1.0, v107
	v_exp_f32_e32 v105, v105
	v_mul_f32_e32 v107, 0xbfb8aa3b, v143
	v_exp_f32_e32 v107, v107
	v_rcp_f32_e32 v145, v98
	v_add_f32_e32 v98, 1.0, v105
	v_rcp_f32_e32 v146, v98
	v_add_f32_e32 v98, 1.0, v107
	v_rcp_f32_e32 v147, v98
	v_pk_mul_f32 v[68:69], v[112:113], v[68:69]
	v_pk_mul_f32 v[126:127], v[126:127], v[134:135]
	v_pk_mul_f32 v[70:71], v[70:71], v[144:145]
	v_pk_mul_f32 v[112:113], v[142:143], v[146:147]
	s_and_saveexec_b64 s[4:5], s[0:1]
	s_cbranch_execz .LBB0_176
	v_pk_mul_f32 v[134:135], v[68:69], v[68:69]
	v_pk_mul_f32 v[142:143], v[126:127], v[126:127]
	v_add_f32_e32 v98, v134, v135
	v_add_f32_e32 v98, v142, v98
	v_pk_mul_f32 v[144:145], v[70:71], v[70:71]
	v_add_f32_e32 v98, v143, v98
	v_add_f32_e32 v98, v144, v98
	v_pk_mul_f32 v[146:147], v[112:113], v[112:113]
	v_add_f32_e32 v98, v145, v98
	v_add_f32_e32 v98, v146, v98
	v_add_f32_e32 v98, v147, v98
	s_nop 1
	v_add_f32_dpp v98, v98, v98 row_ror:8 row_mask:0xf bank_mask:0xf bound_ctrl:1
	s_nop 1
	v_add_f32_dpp v98, v98, v98 row_ror:4 row_mask:0xf bank_mask:0xf bound_ctrl:1
	s_nop 1
	v_add_f32_dpp v98, v98, v98 row_ror:2 row_mask:0xf bank_mask:0xf bound_ctrl:1
	s_nop 1
	v_add_f32_dpp v98, v98, v98 row_ror:1 row_mask:0xf bank_mask:0xf bound_ctrl:1
	v_add_f32_e32 v98, 0x358637bd, v98
	v_mul_f32_e32 v105, 0x4b800000, v98
	v_cmp_gt_f32_e32 vcc, s29, v98
	s_nop 1
	v_cndmask_b32_e32 v98, v98, v105, vcc
	v_rsq_f32_e32 v98, v98
	s_nop 0
	v_mul_f32_e32 v105, 0x45800000, v98
	v_cndmask_b32_e32 v98, v98, v105, vcc
	v_mul_f32_e32 v98, v166, v98
	v_pk_mul_f32 v[68:69], v[68:69], v[98:99] op_sel_hi:[1,0]
	v_pk_mul_f32 v[126:127], v[126:127], v[98:99] op_sel_hi:[1,0]
	v_pk_mul_f32 v[70:71], v[70:71], v[98:99] op_sel_hi:[1,0]
	v_pk_mul_f32 v[112:113], v[112:113], v[98:99] op_sel_hi:[1,0]

; __device__ __forceinline__ void unpack8(const u32x4 w, float (&f)[8]) { f[0] = bf_lo(w.x); f[1] = bf_hi(w.x); f[2] = bf_lo(w.y); f[3] = bf_hi(w.y); f[4] = bf_lo(w.z); f[5] = bf_hi(w.z); f[6] = bf_lo(w.w); f[7] = bf_hi(w.w); }
; __device__ __forceinline__ float siluf_(float x) { return x * __builtin_amdgcn_rcpf(1.0f + __builtin_amdgcn_exp2f(x * -1.4426950408889634f)); }
; __device__ __forceinline__ void phase_qkv(const Args& a) {
;     ...
;         for (int m = 0; m < 16; ++m) {
;             float acc[8];
; #pragma unroll
;             for (int e = 0; e < 8; ++e) acc[e] = 0.f;
;             if (m == 0) { unpack8(R[0], F[0]); unpack8(R[1], F[1]); unpack8(R[2], F[2]); }
;             unpack8(R[m + 3], F[m + 3]);
; #pragma unroll
;             for (int i = 0; i < 4; ++i) {
;                 if (m + i < 3) { const float vm = (pos0 + m + i - 3 >= 0) ? 1.0f : 0.0f;
; #pragma unroll
;                     for (int e = 0; e < 8; ++e) acc[e] += F[m + i][e] * (w[i][e] * vm); }
;                 else {
; #pragma unroll
;                     for (int e = 0; e < 8; ++e) acc[e] += F[m + i][e] * w[i][e]; } }
;             float ssq = 0.f;
; #pragma unroll
;             for (int e = 0; e < 8; ++e) { acc[e] = siluf_(acc[e]); ssq += acc[e] * acc[e]; }
;             if (part < 2) { ssq = sum16(ssq); const float sc = rsqrtf(ssq + EPS) * qsc;
; #pragma unroll
;                 for (int e = 0; e < 8; ++e) acc[e] *= sc; }
.LBB0_178:
	s_or_b64 exec, exec, s[4:5]
	v_and_b32_e32 v113, 0xffff0000, v60
	v_lshlrev_b32_e32 v112, 16, v60
	v_and_b32_e32 v127, 0xffff0000, v61
	v_lshlrev_b32_e32 v126, 16, v61
	v_pk_fma_f32 v[60:61], v[22:23], v[140:141], 0 op_sel_hi:[1,1,0]
	v_pk_fma_f32 v[118:119], v[0:1], v[118:119], 0 op_sel_hi:[1,1,0]
	v_pk_fma_f32 v[60:61], v[26:27], v[138:139], v[60:61]
	v_and_b32_e32 v143, 0xffff0000, v63
	v_lshlrev_b32_e32 v142, 16, v63
	v_pk_fma_f32 v[60:61], v[30:31], v[136:137], v[60:61]
	v_pk_fma_f32 v[118:119], v[4:5], v[116:117], v[118:119]
	v_pk_fma_f32 v[140:141], v[34:35], v[142:143], v[60:61]
	v_pk_fma_f32 v[60:61], v[20:21], v[132:133], 0 op_sel_hi:[1,1,0]
	v_pk_fma_f32 v[118:119], v[12:13], v[114:115], v[118:119]
	v_pk_fma_f32 v[60:61], v[24:25], v[130:131], v[60:61]
	v_pk_fma_f32 v[118:119], v[8:9], v[112:113], v[118:119]
	v_and_b32_e32 v135, 0xffff0000, v62
	v_lshlrev_b32_e32 v134, 16, v62
	v_pk_fma_f32 v[60:61], v[28:29], v[128:129], v[60:61]
	v_mul_f32_e32 v98, 0xbfb8aa3b, v118
	v_pk_fma_f32 v[62:63], v[32:33], v[134:135], v[60:61]
	v_pk_fma_f32 v[60:61], v[2:3], v[124:125], 0 op_sel_hi:[1,1,0]
	v_exp_f32_e32 v98, v98
	v_mul_f32_e32 v105, 0xbfb8aa3b, v119
	v_pk_fma_f32 v[60:61], v[6:7], v[122:123], v[60:61]
	v_exp_f32_e32 v105, v105
	v_pk_fma_f32 v[60:61], v[14:15], v[120:121], v[60:61]
	v_mul_f32_e32 v107, 0xbfb8aa3b, v63
	v_pk_fma_f32 v[124:125], v[10:11], v[126:127], v[60:61]
	v_add_f32_e32 v60, 1.0, v98
	v_mul_f32_e32 v98, 0xbfb8aa3b, v124
	v_add_f32_e32 v61, 1.0, v105
	v_exp_f32_e32 v98, v98
	v_mul_f32_e32 v105, 0xbfb8aa3b, v125
	v_exp_f32_e32 v105, v105
	v_exp_f32_e32 v107, v107
	v_add_f32_e32 v98, 1.0, v98
	v_rcp_f32_e32 v132, v98
	v_add_f32_e32 v98, 1.0, v105
	v_mul_f32_e32 v105, 0xbfb8aa3b, v62
	v_exp_f32_e32 v105, v105
	v_rcp_f32_e32 v133, v98
	v_rcp_f32_e32 v60, v60
	v_rcp_f32_e32 v61, v61
	v_add_f32_e32 v98, 1.0, v105
	v_mul_f32_e32 v105, 0xbfb8aa3b, v140
	v_rcp_f32_e32 v144, v98
	v_add_f32_e32 v98, 1.0, v107
	v_exp_f32_e32 v105, v105
	v_mul_f32_e32 v107, 0xbfb8aa3b, v141
	v_exp_f32_e32 v107, v107
	v_rcp_f32_e32 v145, v98
	v_add_f32_e32 v98, 1.0, v105
	v_rcp_f32_e32 v146, v98
	v_add_f32_e32 v98, 1.0, v107
	v_rcp_f32_e32 v147, v98
	v_pk_mul_f32 v[60:61], v[118:119], v[60:61]
	v_pk_mul_f32 v[124:125], v[124:125], v[132:133]
	v_pk_mul_f32 v[62:63], v[62:63], v[144:145]
	v_pk_mul_f32 v[118:119], v[140:141], v[146:147]
	s_and_saveexec_b64 s[4:5], s[0:1]
	s_cbranch_execz .LBB0_180
	v_pk_mul_f32 v[132:133], v[60:61], v[60:61]
	v_pk_mul_f32 v[140:141], v[124:125], v[124:125]
	v_add_f32_e32 v98, v132, v133
	v_add_f32_e32 v98, v140, v98
	v_pk_mul_f32 v[144:145], v[62:63], v[62:63]
	v_add_f32_e32 v98, v141, v98
	v_add_f32_e32 v98, v144, v98
	v_pk_mul_f32 v[146:147], v[118:119], v[118:119]
	v_add_f32_e32 v98, v145, v98
	v_add_f32_e32 v98, v146, v98
	v_add_f32_e32 v98, v147, v98
	s_nop 1
	v_add_f32_dpp v98, v98, v98 row_ror:8 row_mask:0xf bank_mask:0xf bound_ctrl:1
	s_nop 1
	v_add_f32_dpp v98, v98, v98 row_ror:4 row_mask:0xf bank_mask:0xf bound_ctrl:1
	s_nop 1
	v_add_f32_dpp v98, v98, v98 row_ror:2 row_mask:0xf bank_mask:0xf bound_ctrl:1
	s_nop 1
	v_add_f32_dpp v98, v98, v98 row_ror:1 row_mask:0xf bank_mask:0xf bound_ctrl:1
	v_add_f32_e32 v98, 0x358637bd, v98
	v_mul_f32_e32 v105, 0x4b800000, v98
	v_cmp_gt_f32_e32 vcc, s29, v98
	s_nop 1
	v_cndmask_b32_e32 v98, v98, v105, vcc
	v_rsq_f32_e32 v98, v98
	s_nop 0
	v_mul_f32_e32 v105, 0x45800000, v98
	v_cndmask_b32_e32 v98, v98, v105, vcc
	v_mul_f32_e32 v98, v166, v98
	v_pk_mul_f32 v[60:61], v[60:61], v[98:99] op_sel_hi:[1,0]
	v_pk_mul_f32 v[124:125], v[124:125], v[98:99] op_sel_hi:[1,0]
	v_pk_mul_f32 v[62:63], v[62:63], v[98:99] op_sel_hi:[1,0]
	v_pk_mul_f32 v[118:119], v[118:119], v[98:99] op_sel_hi:[1,0]

; __device__ __forceinline__ void unpack8(const u32x4 w, float (&f)[8]) { f[0] = bf_lo(w.x); f[1] = bf_hi(w.x); f[2] = bf_lo(w.y); f[3] = bf_hi(w.y); f[4] = bf_lo(w.z); f[5] = bf_hi(w.z); f[6] = bf_lo(w.w); f[7] = bf_hi(w.w); }
; __device__ __forceinline__ float siluf_(float x) { return x * __builtin_amdgcn_rcpf(1.0f + __builtin_amdgcn_exp2f(x * -1.4426950408889634f)); }
; __device__ __forceinline__ void phase_qkv(const Args& a) {
;     ...
;         for (int m = 0; m < 16; ++m) {
;             float acc[8];
; #pragma unroll
;             for (int e = 0; e < 8; ++e) acc[e] = 0.f;
;             if (m == 0) { unpack8(R[0], F[0]); unpack8(R[1], F[1]); unpack8(R[2], F[2]); }
;             unpack8(R[m + 3], F[m + 3]);
; #pragma unroll
;             for (int i = 0; i < 4; ++i) {
;                 if (m + i < 3) { const float vm = (pos0 + m + i - 3 >= 0) ? 1.0f : 0.0f;
; #pragma unroll
;                     for (int e = 0; e < 8; ++e) acc[e] += F[m + i][e] * (w[i][e] * vm); }
;                 else {
; #pragma unroll
;                     for (int e = 0; e < 8; ++e) acc[e] += F[m + i][e] * w[i][e]; } }
;             float ssq = 0.f;
; #pragma unroll
;             for (int e = 0; e < 8; ++e) { acc[e] = siluf_(acc[e]); ssq += acc[e] * acc[e]; }
;             if (part < 2) { ssq = sum16(ssq); const float sc = rsqrtf(ssq + EPS) * qsc;
; #pragma unroll
;                 for (int e = 0; e < 8; ++e) acc[e] *= sc; }
.LBB0_182:
	s_or_b64 exec, exec, s[4:5]
	v_and_b32_e32 v119, 0xffff0000, v52
	v_lshlrev_b32_e32 v118, 16, v52
	v_and_b32_e32 v125, 0xffff0000, v53
	v_lshlrev_b32_e32 v124, 16, v53
	v_pk_fma_f32 v[52:53], v[22:23], v[138:139], 0 op_sel_hi:[1,1,0]
	v_pk_fma_f32 v[116:117], v[0:1], v[116:117], 0 op_sel_hi:[1,1,0]
	v_pk_fma_f32 v[52:53], v[26:27], v[136:137], v[52:53]
	v_and_b32_e32 v141, 0xffff0000, v55
	v_lshlrev_b32_e32 v140, 16, v55
	v_pk_fma_f32 v[52:53], v[30:31], v[142:143], v[52:53]
	v_pk_fma_f32 v[116:117], v[4:5], v[114:115], v[116:117]
	v_pk_fma_f32 v[138:139], v[34:35], v[140:141], v[52:53]
	v_pk_fma_f32 v[52:53], v[20:21], v[130:131], 0 op_sel_hi:[1,1,0]
	v_pk_fma_f32 v[116:117], v[12:13], v[112:113], v[116:117]
	v_pk_fma_f32 v[52:53], v[24:25], v[128:129], v[52:53]
	v_pk_fma_f32 v[116:117], v[8:9], v[118:119], v[116:117]
	v_and_b32_e32 v133, 0xffff0000, v54
	v_lshlrev_b32_e32 v132, 16, v54
	v_pk_fma_f32 v[52:53], v[28:29], v[134:135], v[52:53]
	v_mul_f32_e32 v98, 0xbfb8aa3b, v116
	v_pk_fma_f32 v[54:55], v[32:33], v[132:133], v[52:53]
	v_pk_fma_f32 v[52:53], v[2:3], v[122:123], 0 op_sel_hi:[1,1,0]
	v_exp_f32_e32 v98, v98
	v_mul_f32_e32 v105, 0xbfb8aa3b, v117
	v_pk_fma_f32 v[52:53], v[6:7], v[120:121], v[52:53]
	v_exp_f32_e32 v105, v105
	v_pk_fma_f32 v[52:53], v[14:15], v[126:127], v[52:53]
	v_mul_f32_e32 v107, 0xbfb8aa3b, v55
	v_pk_fma_f32 v[122:123], v[10:11], v[124:125], v[52:53]
	v_add_f32_e32 v52, 1.0, v98
	v_mul_f32_e32 v98, 0xbfb8aa3b, v122
	v_add_f32_e32 v53, 1.0, v105
	v_exp_f32_e32 v98, v98
	v_mul_f32_e32 v105, 0xbfb8aa3b, v123
	v_exp_f32_e32 v105, v105
	v_exp_f32_e32 v107, v107
	v_add_f32_e32 v98, 1.0, v98
	v_rcp_f32_e32 v130, v98
	v_add_f32_e32 v98, 1.0, v105
	v_mul_f32_e32 v105, 0xbfb8aa3b, v54
	v_exp_f32_e32 v105, v105
	v_rcp_f32_e32 v131, v98
	v_rcp_f32_e32 v52, v52
	v_rcp_f32_e32 v53, v53
	v_add_f32_e32 v98, 1.0, v105
	v_mul_f32_e32 v105, 0xbfb8aa3b, v138
	v_rcp_f32_e32 v144, v98
	v_add_f32_e32 v98, 1.0, v107
	v_exp_f32_e32 v105, v105
	v_mul_f32_e32 v107, 0xbfb8aa3b, v139
	v_exp_f32_e32 v107, v107
	v_rcp_f32_e32 v145, v98
	v_add_f32_e32 v98, 1.0, v105
	v_rcp_f32_e32 v146, v98
	v_add_f32_e32 v98, 1.0, v107
	v_rcp_f32_e32 v147, v98
	v_pk_mul_f32 v[52:53], v[116:117], v[52:53]
	v_pk_mul_f32 v[122:123], v[122:123], v[130:131]
	v_pk_mul_f32 v[54:55], v[54:55], v[144:145]
	v_pk_mul_f32 v[116:117], v[138:139], v[146:147]
	s_and_saveexec_b64 s[4:5], s[0:1]
	s_cbranch_execz .LBB0_184
	v_pk_mul_f32 v[130:131], v[52:53], v[52:53]
	v_pk_mul_f32 v[138:139], v[122:123], v[122:123]
	v_add_f32_e32 v98, v130, v131
	v_add_f32_e32 v98, v138, v98
	v_pk_mul_f32 v[144:145], v[54:55], v[54:55]
	v_add_f32_e32 v98, v139, v98
	v_add_f32_e32 v98, v144, v98
	v_pk_mul_f32 v[146:147], v[116:117], v[116:117]
	v_add_f32_e32 v98, v145, v98
	v_add_f32_e32 v98, v146, v98
	v_add_f32_e32 v98, v147, v98
	s_nop 1
	v_add_f32_dpp v98, v98, v98 row_ror:8 row_mask:0xf bank_mask:0xf bound_ctrl:1
	s_nop 1
	v_add_f32_dpp v98, v98, v98 row_ror:4 row_mask:0xf bank_mask:0xf bound_ctrl:1
	s_nop 1
	v_add_f32_dpp v98, v98, v98 row_ror:2 row_mask:0xf bank_mask:0xf bound_ctrl:1
	s_nop 1
	v_add_f32_dpp v98, v98, v98 row_ror:1 row_mask:0xf bank_mask:0xf bound_ctrl:1
	v_add_f32_e32 v98, 0x358637bd, v98
	v_mul_f32_e32 v105, 0x4b800000, v98
	v_cmp_gt_f32_e32 vcc, s29, v98
	s_nop 1
	v_cndmask_b32_e32 v98, v98, v105, vcc
	v_rsq_f32_e32 v98, v98
	s_nop 0
	v_mul_f32_e32 v105, 0x45800000, v98
	v_cndmask_b32_e32 v98, v98, v105, vcc
	v_mul_f32_e32 v98, v166, v98
	v_pk_mul_f32 v[52:53], v[52:53], v[98:99] op_sel_hi:[1,0]
	v_pk_mul_f32 v[122:123], v[122:123], v[98:99] op_sel_hi:[1,0]
	v_pk_mul_f32 v[54:55], v[54:55], v[98:99] op_sel_hi:[1,0]
	v_pk_mul_f32 v[116:117], v[116:117], v[98:99] op_sel_hi:[1,0]

; __device__ __forceinline__ void unpack8(const u32x4 w, float (&f)[8]) { f[0] = bf_lo(w.x); f[1] = bf_hi(w.x); f[2] = bf_lo(w.y); f[3] = bf_hi(w.y); f[4] = bf_lo(w.z); f[5] = bf_hi(w.z); f[6] = bf_lo(w.w); f[7] = bf_hi(w.w); }
; __device__ __forceinline__ float siluf_(float x) { return x * __builtin_amdgcn_rcpf(1.0f + __builtin_amdgcn_exp2f(x * -1.4426950408889634f)); }
; __device__ __forceinline__ void phase_qkv(const Args& a) {
;     ...
;         for (int m = 0; m < 16; ++m) {
;             float acc[8];
; #pragma unroll
;             for (int e = 0; e < 8; ++e) acc[e] = 0.f;
;             if (m == 0) { unpack8(R[0], F[0]); unpack8(R[1], F[1]); unpack8(R[2], F[2]); }
;             unpack8(R[m + 3], F[m + 3]);
; #pragma unroll
;             for (int i = 0; i < 4; ++i) {
;                 if (m + i < 3) { const float vm = (pos0 + m + i - 3 >= 0) ? 1.0f : 0.0f;
; #pragma unroll
;                     for (int e = 0; e < 8; ++e) acc[e] += F[m + i][e] * (w[i][e] * vm); }
;                 else {
; #pragma unroll
;                     for (int e = 0; e < 8; ++e) acc[e] += F[m + i][e] * w[i][e]; } }
;             float ssq = 0.f;
; #pragma unroll
;             for (int e = 0; e < 8; ++e) { acc[e] = siluf_(acc[e]); ssq += acc[e] * acc[e]; }
;             if (part < 2) { ssq = sum16(ssq); const float sc = rsqrtf(ssq + EPS) * qsc;
; #pragma unroll
;                 for (int e = 0; e < 8; ++e) acc[e] *= sc; }
.LBB0_186:
	s_or_b64 exec, exec, s[4:5]
	v_and_b32_e32 v117, 0xffff0000, v44
	v_lshlrev_b32_e32 v116, 16, v44
	v_and_b32_e32 v123, 0xffff0000, v45
	v_lshlrev_b32_e32 v122, 16, v45
	v_pk_fma_f32 v[44:45], v[22:23], v[136:137], 0 op_sel_hi:[1,1,0]
	v_pk_fma_f32 v[114:115], v[0:1], v[114:115], 0 op_sel_hi:[1,1,0]
	v_pk_fma_f32 v[44:45], v[26:27], v[142:143], v[44:45]
	v_and_b32_e32 v139, 0xffff0000, v47
	v_lshlrev_b32_e32 v138, 16, v47
	v_pk_fma_f32 v[44:45], v[30:31], v[140:141], v[44:45]
	v_pk_fma_f32 v[114:115], v[4:5], v[112:113], v[114:115]
	v_pk_fma_f32 v[136:137], v[34:35], v[138:139], v[44:45]
	v_pk_fma_f32 v[44:45], v[20:21], v[128:129], 0 op_sel_hi:[1,1,0]
	v_pk_fma_f32 v[114:115], v[12:13], v[118:119], v[114:115]
	v_pk_fma_f32 v[44:45], v[24:25], v[134:135], v[44:45]
	v_pk_fma_f32 v[114:115], v[8:9], v[116:117], v[114:115]
	v_and_b32_e32 v131, 0xffff0000, v46
	v_lshlrev_b32_e32 v130, 16, v46
	v_pk_fma_f32 v[44:45], v[28:29], v[132:133], v[44:45]
	v_mul_f32_e32 v98, 0xbfb8aa3b, v114
	v_pk_fma_f32 v[46:47], v[32:33], v[130:131], v[44:45]
	v_pk_fma_f32 v[44:45], v[2:3], v[120:121], 0 op_sel_hi:[1,1,0]
	v_exp_f32_e32 v98, v98
	v_mul_f32_e32 v105, 0xbfb8aa3b, v115
	v_pk_fma_f32 v[44:45], v[6:7], v[126:127], v[44:45]
	v_exp_f32_e32 v105, v105
	v_pk_fma_f32 v[44:45], v[14:15], v[124:125], v[44:45]
	v_mul_f32_e32 v107, 0xbfb8aa3b, v47
	v_pk_fma_f32 v[120:121], v[10:11], v[122:123], v[44:45]
	v_add_f32_e32 v44, 1.0, v98
	v_mul_f32_e32 v98, 0xbfb8aa3b, v120
	v_add_f32_e32 v45, 1.0, v105
	v_exp_f32_e32 v98, v98
	v_mul_f32_e32 v105, 0xbfb8aa3b, v121
	v_exp_f32_e32 v105, v105
	v_exp_f32_e32 v107, v107
	v_add_f32_e32 v98, 1.0, v98
	v_rcp_f32_e32 v128, v98
	v_add_f32_e32 v98, 1.0, v105
	v_mul_f32_e32 v105, 0xbfb8aa3b, v46
	v_exp_f32_e32 v105, v105
	v_rcp_f32_e32 v129, v98
	v_rcp_f32_e32 v44, v44
	v_rcp_f32_e32 v45, v45
	v_add_f32_e32 v98, 1.0, v105
	v_mul_f32_e32 v105, 0xbfb8aa3b, v136
	v_rcp_f32_e32 v144, v98
	v_add_f32_e32 v98, 1.0, v107
	v_exp_f32_e32 v105, v105
	v_mul_f32_e32 v107, 0xbfb8aa3b, v137
	v_exp_f32_e32 v107, v107
	v_rcp_f32_e32 v145, v98
	v_add_f32_e32 v98, 1.0, v105
	v_rcp_f32_e32 v146, v98
	v_add_f32_e32 v98, 1.0, v107
	v_rcp_f32_e32 v147, v98
	v_pk_mul_f32 v[44:45], v[114:115], v[44:45]
	v_pk_mul_f32 v[120:121], v[120:121], v[128:129]
	v_pk_mul_f32 v[46:47], v[46:47], v[144:145]
	v_pk_mul_f32 v[114:115], v[136:137], v[146:147]
	s_and_saveexec_b64 s[4:5], s[0:1]
	s_cbranch_execz .LBB0_188
	v_pk_mul_f32 v[128:129], v[44:45], v[44:45]
	v_pk_mul_f32 v[136:137], v[120:121], v[120:121]
	v_add_f32_e32 v98, v128, v129
	v_add_f32_e32 v98, v136, v98
	v_pk_mul_f32 v[144:145], v[46:47], v[46:47]
	v_add_f32_e32 v98, v137, v98
	v_add_f32_e32 v98, v144, v98
	v_pk_mul_f32 v[146:147], v[114:115], v[114:115]
	v_add_f32_e32 v98, v145, v98
	v_add_f32_e32 v98, v146, v98
	v_add_f32_e32 v98, v147, v98
	s_nop 1
	v_add_f32_dpp v98, v98, v98 row_ror:8 row_mask:0xf bank_mask:0xf bound_ctrl:1
	s_nop 1
	v_add_f32_dpp v98, v98, v98 row_ror:4 row_mask:0xf bank_mask:0xf bound_ctrl:1
	s_nop 1
	v_add_f32_dpp v98, v98, v98 row_ror:2 row_mask:0xf bank_mask:0xf bound_ctrl:1
	s_nop 1
	v_add_f32_dpp v98, v98, v98 row_ror:1 row_mask:0xf bank_mask:0xf bound_ctrl:1
	v_add_f32_e32 v98, 0x358637bd, v98
	v_mul_f32_e32 v105, 0x4b800000, v98
	v_cmp_gt_f32_e32 vcc, s29, v98
	s_nop 1
	v_cndmask_b32_e32 v98, v98, v105, vcc
	v_rsq_f32_e32 v98, v98
	s_nop 0
	v_mul_f32_e32 v105, 0x45800000, v98
	v_cndmask_b32_e32 v98, v98, v105, vcc
	v_mul_f32_e32 v98, v166, v98
	v_pk_mul_f32 v[44:45], v[44:45], v[98:99] op_sel_hi:[1,0]
	v_pk_mul_f32 v[120:121], v[120:121], v[98:99] op_sel_hi:[1,0]
	v_pk_mul_f32 v[46:47], v[46:47], v[98:99] op_sel_hi:[1,0]
	v_pk_mul_f32 v[114:115], v[114:115], v[98:99] op_sel_hi:[1,0]

; __device__ __forceinline__ void unpack8(const u32x4 w, float (&f)[8]) { f[0] = bf_lo(w.x); f[1] = bf_hi(w.x); f[2] = bf_lo(w.y); f[3] = bf_hi(w.y); f[4] = bf_lo(w.z); f[5] = bf_hi(w.z); f[6] = bf_lo(w.w); f[7] = bf_hi(w.w); }
; __device__ __forceinline__ float siluf_(float x) { return x * __builtin_amdgcn_rcpf(1.0f + __builtin_amdgcn_exp2f(x * -1.4426950408889634f)); }
; __device__ __forceinline__ void phase_qkv(const Args& a) {
;     ...
;         for (int m = 0; m < 16; ++m) {
;             float acc[8];
; #pragma unroll
;             for (int e = 0; e < 8; ++e) acc[e] = 0.f;
;             if (m == 0) { unpack8(R[0], F[0]); unpack8(R[1], F[1]); unpack8(R[2], F[2]); }
;             unpack8(R[m + 3], F[m + 3]);
; #pragma unroll
;             for (int i = 0; i < 4; ++i) {
;                 if (m + i < 3) { const float vm = (pos0 + m + i - 3 >= 0) ? 1.0f : 0.0f;
; #pragma unroll
;                     for (int e = 0; e < 8; ++e) acc[e] += F[m + i][e] * (w[i][e] * vm); }
;                 else {
; #pragma unroll
;                     for (int e = 0; e < 8; ++e) acc[e] += F[m + i][e] * w[i][e]; } }
;             float ssq = 0.f;
; #pragma unroll
;             for (int e = 0; e < 8; ++e) { acc[e] = siluf_(acc[e]); ssq += acc[e] * acc[e]; }
;             if (part < 2) { ssq = sum16(ssq); const float sc = rsqrtf(ssq + EPS) * qsc;
; #pragma unroll
;                 for (int e = 0; e < 8; ++e) acc[e] *= sc; }
.LBB0_190:
	s_or_b64 exec, exec, s[4:5]
	v_pk_fma_f32 v[22:23], v[22:23], v[142:143], 0 op_sel_hi:[1,1,0]
	v_pk_fma_f32 v[20:21], v[20:21], v[134:135], 0 op_sel_hi:[1,1,0]
	v_pk_fma_f32 v[2:3], v[2:3], v[126:127], 0 op_sel_hi:[1,1,0]
	v_pk_fma_f32 v[0:1], v[0:1], v[112:113], 0 op_sel_hi:[1,1,0]
	v_pk_fma_f32 v[22:23], v[26:27], v[140:141], v[22:23]
	v_pk_fma_f32 v[20:21], v[24:25], v[132:133], v[20:21]
	v_pk_fma_f32 v[2:3], v[6:7], v[124:125], v[2:3]
	v_pk_fma_f32 v[0:1], v[4:5], v[118:119], v[0:1]
	v_and_b32_e32 v115, 0xffff0000, v39
	v_lshlrev_b32_e32 v114, 16, v39
	v_pk_fma_f32 v[22:23], v[30:31], v[138:139], v[22:23]
	v_and_b32_e32 v27, 0xffff0000, v38
	v_lshlrev_b32_e32 v26, 16, v38
	v_pk_fma_f32 v[20:21], v[28:29], v[130:131], v[20:21]
	v_and_b32_e32 v25, 0xffff0000, v37
	v_lshlrev_b32_e32 v24, 16, v37
	v_pk_fma_f32 v[2:3], v[14:15], v[122:123], v[2:3]
	v_and_b32_e32 v7, 0xffff0000, v36
	v_lshlrev_b32_e32 v6, 16, v36
	v_pk_fma_f32 v[0:1], v[12:13], v[116:117], v[0:1]
	v_pk_fma_f32 v[22:23], v[34:35], v[114:115], v[22:23]
	v_pk_fma_f32 v[20:21], v[32:33], v[26:27], v[20:21]
	v_pk_fma_f32 v[0:1], v[8:9], v[6:7], v[0:1]
	v_pk_fma_f32 v[2:3], v[10:11], v[24:25], v[2:3]
	v_mul_f32_e32 v4, 0xbfb8aa3b, v0
	v_mul_f32_e32 v5, 0xbfb8aa3b, v1
	v_mul_f32_e32 v6, 0xbfb8aa3b, v2
	v_mul_f32_e32 v7, 0xbfb8aa3b, v3
	v_mul_f32_e32 v8, 0xbfb8aa3b, v20
	v_mul_f32_e32 v9, 0xbfb8aa3b, v21
	v_mul_f32_e32 v10, 0xbfb8aa3b, v22
	v_mul_f32_e32 v11, 0xbfb8aa3b, v23
	v_exp_f32_e32 v4, v4
	v_exp_f32_e32 v5, v5
	v_exp_f32_e32 v6, v6
	v_exp_f32_e32 v7, v7
	v_exp_f32_e32 v8, v8
	v_exp_f32_e32 v9, v9
	v_exp_f32_e32 v10, v10
	v_exp_f32_e32 v11, v11
	v_add_f32_e32 v4, 1.0, v4
	v_add_f32_e32 v5, 1.0, v5
	v_add_f32_e32 v6, 1.0, v6
	v_add_f32_e32 v7, 1.0, v7
	v_add_f32_e32 v8, 1.0, v8
	v_add_f32_e32 v9, 1.0, v9
	v_add_f32_e32 v10, 1.0, v10
	v_add_f32_e32 v11, 1.0, v11
	v_rcp_f32_e32 v4, v4
	v_rcp_f32_e32 v5, v5
	v_rcp_f32_e32 v6, v6
	v_rcp_f32_e32 v7, v7
	v_rcp_f32_e32 v8, v8
	v_rcp_f32_e32 v9, v9
	v_rcp_f32_e32 v10, v10
	v_rcp_f32_e32 v11, v11
	v_pk_mul_f32 v[0:1], v[0:1], v[4:5]
	v_pk_mul_f32 v[6:7], v[2:3], v[6:7]
	v_pk_mul_f32 v[2:3], v[20:21], v[8:9]
	v_pk_mul_f32 v[4:5], v[22:23], v[10:11]
	s_and_saveexec_b64 s[4:5], s[0:1]
	s_cbranch_execz .LBB0_192
	v_pk_mul_f32 v[8:9], v[0:1], v[0:1]
	v_pk_mul_f32 v[10:11], v[6:7], v[6:7]
	v_add_f32_e32 v8, v8, v9
	v_add_f32_e32 v8, v10, v8
	v_pk_mul_f32 v[12:13], v[2:3], v[2:3]
	v_add_f32_e32 v8, v11, v8
	v_add_f32_e32 v8, v12, v8
	v_pk_mul_f32 v[14:15], v[4:5], v[4:5]
	v_add_f32_e32 v8, v13, v8
	v_add_f32_e32 v8, v14, v8
	v_add_f32_e32 v8, v15, v8
	s_nop 1
	v_add_f32_dpp v8, v8, v8 row_ror:8 row_mask:0xf bank_mask:0xf bound_ctrl:1
	s_nop 1
	v_add_f32_dpp v8, v8, v8 row_ror:4 row_mask:0xf bank_mask:0xf bound_ctrl:1
	s_nop 1
	v_add_f32_dpp v8, v8, v8 row_ror:2 row_mask:0xf bank_mask:0xf bound_ctrl:1
	s_nop 1
	v_add_f32_dpp v8, v8, v8 row_ror:1 row_mask:0xf bank_mask:0xf bound_ctrl:1
	v_add_f32_e32 v8, 0x358637bd, v8
	v_mul_f32_e32 v9, 0x4b800000, v8
	v_cmp_gt_f32_e32 vcc, s29, v8
	s_nop 1
	v_cndmask_b32_e32 v8, v8, v9, vcc
	v_rsq_f32_e32 v8, v8
	s_nop 0
	v_mul_f32_e32 v9, 0x45800000, v8
	v_cndmask_b32_e32 v8, v8, v9, vcc
	v_mul_f32_e32 v8, v166, v8
	v_pk_mul_f32 v[0:1], v[0:1], v[8:9] op_sel_hi:[1,0]
	v_pk_mul_f32 v[6:7], v[6:7], v[8:9] op_sel_hi:[1,0]
	v_pk_mul_f32 v[2:3], v[2:3], v[8:9] op_sel_hi:[1,0]
	v_pk_mul_f32 v[4:5], v[4:5], v[8:9] op_sel_hi:[1,0]
